# v2 (PV x11 deferred past the barrier, hoisted fragment addresses) + s_setprio ladder
# baseline (speedup 1.0000x reference)
.LBB0_529:
	v_mov_b32_e32 v0, v1
	s_ashr_i32 s43, s39, 3
	v_mbcnt_lo_u32_b32 v0, -1, v0
	v_mbcnt_hi_u32_b32 v0, -1, v0
	v_add_u32_e32 v138, s54, v0
	s_sub_i32 s21, 63, s43
	v_readfirstlane_b32 s22, v138
	s_ashr_i32 s23, s22, 6
	s_lshl_b32 s8, s21, 8
	s_lshl_b32 s6, s23, 5
	s_and_b32 s9, s39, 7
	v_and_b32_e32 v215, 31, v138
	s_add_i32 s20, s6, s8
	v_or_b32_e32 v2, s20, v215
	v_mov_b64_e32 v[4:5], s[70:71]
	s_mul_i32 s45, s9, 0xc0
	v_bfe_u32 v214, v138, 5, 1
	v_mad_i64_i32 v[4:5], s[10:11], v2, s46, v[4:5]
	s_lshl_b32 s86, s45, 1
	v_ashrrev_i32_e32 v3, 31, v2
	v_lshl_add_u64 v[4:5], v[4:5], 0, s[86:87]
	v_lshlrev_b32_e32 v0, 4, v214
	v_lshl_add_u64 v[4:5], v[4:5], 0, v[0:1]
	v_lshl_add_u64 v[2:3], v[2:3], 2, s[68:69]
	global_load_dwordx4 v[110:113], v[4:5], off
	global_load_dwordx4 v[106:109], v[4:5], off offset:32
	global_load_dwordx4 v[102:105], v[4:5], off offset:64
	global_load_dwordx4 v[98:101], v[4:5], off offset:96
	global_load_dwordx4 v[94:97], v[4:5], off offset:128
	global_load_dwordx4 v[90:93], v[4:5], off offset:160
	global_load_dwordx4 v[86:89], v[4:5], off offset:192
	global_load_dwordx4 v[82:85], v[4:5], off offset:224
	global_load_dwordx4 v[78:81], v[4:5], off offset:256
	global_load_dwordx4 v[118:121], v[4:5], off offset:288
	global_load_dwordx4 v[74:77], v[4:5], off offset:320
	global_load_dwordx4 v[114:117], v[4:5], off offset:352
	global_load_dword v142, v[2:3], off
	v_and_b32_e32 v2, 64, v233
	v_and_b32_e32 v212, 32, v138
	v_add_u32_e32 v216, 64, v2
	global_load_dwordx4 v[2:5], v212, s[24:25] offset:16
	global_load_dwordx4 v[6:9], v212, s[24:25]
	global_load_dwordx4 v[10:13], v212, s[24:25] offset:80
	global_load_dwordx4 v[14:17], v212, s[24:25] offset:64
	global_load_dwordx4 v[122:125], v212, s[26:27] offset:256
	global_load_dwordx4 v[18:21], v212, s[24:25] offset:144
	global_load_dwordx4 v[22:25], v212, s[24:25] offset:128
	global_load_dwordx4 v[126:129], v212, s[26:27] offset:240
	global_load_dwordx4 v[26:29], v212, s[24:25] offset:208
	global_load_dwordx4 v[30:33], v212, s[24:25] offset:192
	global_load_dwordx4 v[34:37], v212, s[24:25] offset:272
	global_load_dwordx4 v[38:41], v212, s[24:25] offset:256
	global_load_dwordx4 v[42:45], v212, s[24:25] offset:336
	global_load_dwordx4 v[46:49], v212, s[24:25] offset:320
	global_load_dwordx4 v[50:53], v212, s[24:25] offset:384
	global_load_dwordx4 v[54:57], v212, s[24:25] offset:512
	global_load_dwordx4 v[130:133], v212, s[26:27] offset:192
	global_load_dwordx4 v[134:137], v212, s[26:27] offset:176
	global_load_dwordx4 v[58:61], v212, s[24:25] offset:576
	global_load_dwordx4 v[70:73], v212, s[24:25] offset:592
	global_load_dwordx4 v[62:65], v212, s[24:25] offset:704
	global_load_dwordx4 v[66:69], v212, s[24:25] offset:720
	v_xor_b32_e32 v0, 32, v233
	v_cmp_lt_i32_e32 vcc, v0, v216
	s_lshl_b32 s10, s23, 2
	v_bfe_u32 v140, v138, 3, 1
	v_cndmask_b32_e32 v0, v233, v0, vcc
	v_lshlrev_b32_e32 v231, 2, v0
	v_bfe_u32 v0, v138, 4, 2
	v_or_b32_e32 v139, s10, v0
	v_lshlrev_b32_e32 v141, 1, v139
	v_and_b32_e32 v217, 63, v138
	v_bitop3_b32 v0, s10, v138, v0 bitop3:0x36
	v_or_b32_e32 v143, v141, v140
	v_mov_b64_e32 v[138:139], s[66:67]
	v_mad_i64_i32 v[138:139], s[10:11], v143, s46, v[138:139]
	v_lshlrev_b32_e32 v0, 4, v0
	v_lshl_add_u64 v[138:139], v[138:139], 0, s[86:87]
	v_and_b32_e32 v0, 0x70, v0
	s_lshl_b32 s44, s9, 7
	v_lshl_add_u64 v[180:181], v[138:139], 0, v[0:1]
	v_add_u32_e32 v138, s44, v141
	s_lshl_b32 s9, s23, 10
	v_or_b32_e32 v138, v138, v140
	s_add_i32 s9, s9, 0
	v_ashrrev_i32_e32 v139, 31, v138
	s_mov_b32 m0, s9
	v_lshlrev_b64 v[138:139], 15, v[138:139]
	global_load_lds_dwordx4 v[180:181], off
	v_lshl_add_u64 v[140:141], v[180:181], 0, s[94:95]
	s_add_i32 m0, s9, 0x2000
	v_lshl_add_u64 v[138:139], s[12:13], 0, v[138:139]
	global_load_lds_dwordx4 v[140:141], off
	v_lshl_add_u64 v[140:141], v[180:181], 0, s[96:97]
	s_add_i32 m0, s9, 0x4000
	v_lshl_add_u64 v[182:183], v[138:139], 0, v[0:1]
	global_load_lds_dwordx4 v[140:141], off
	s_add_i32 m0, s9, 0x6000
	v_lshl_add_u64 v[138:139], v[182:183], 0, s[92:93]
	global_load_lds_dwordx4 v[182:183], off
	s_add_i32 m0, s9, 0x8000
	s_mov_b64 s[10:11], 0x30000
	global_load_lds_dwordx4 v[138:139], off
	v_lshl_add_u64 v[138:139], v[180:181], 0, s[10:11]
	s_add_i32 m0, s9, 0xa000
	s_mov_b64 s[10:11], 0x30080
	global_load_lds_dwordx4 v[138:139], off
	v_lshl_add_u64 v[138:139], v[180:181], 0, s[10:11]
	s_add_i32 m0, s9, 0xc000
	s_mov_b64 s[10:11], 0x30100
	global_load_lds_dwordx4 v[138:139], off
	v_lshl_add_u64 v[138:139], v[180:181], 0, s[10:11]
	s_add_i32 m0, s9, 0xe000
	s_mov_b64 s[10:11], 0x200080
	global_load_lds_dwordx4 v[138:139], off
	s_add_i32 m0, s9, 0x10000
	v_lshl_add_u64 v[138:139], v[182:183], 0, s[94:95]
	global_load_lds_dwordx4 v[138:139], off
	v_lshl_add_u64 v[138:139], v[182:183], 0, s[10:11]
	s_add_i32 m0, s9, 0x12000
	s_waitcnt vmcnt(0)
	v_lshlrev_b32_e32 v148, 16, v107
	global_load_lds_dwordx4 v[138:139], off
	v_and_b32_e32 v149, 0xffff0000, v107
	v_and_b32_e32 v195, 0xffff0000, v121
	v_and_b32_e32 v203, 0xffff0000, v120
	v_lshlrev_b32_e32 v194, 16, v121
	v_cvt_f32_i32_e32 v0, v142
	v_lshlrev_b32_e32 v202, 16, v120
	v_and_b32_e32 v189, 0xffff0000, v117
	v_mov_b32_e32 v120, v194
	v_mul_f32_e32 v125, v125, v0
	v_cvt_f64_f32_e32 v[138:139], v125
	v_mul_f64 v[140:141], v[138:139], s[84:85]
	v_rndne_f64_e32 v[140:141], v[140:141]
	v_fma_f64 v[138:139], v[138:139], s[84:85], -v[140:141]
	v_cvt_f32_f64_e32 v125, v[138:139]
	v_mul_f32_e32 v124, v124, v0
	v_cos_f32_e32 v145, v125
	v_sin_f32_e32 v147, v125
	v_cvt_f64_f32_e32 v[124:125], v124
	v_mul_f64 v[138:139], v[124:125], s[84:85]
	v_rndne_f64_e32 v[138:139], v[138:139]
	v_fma_f64 v[124:125], v[124:125], s[84:85], -v[138:139]
	v_cvt_f32_f64_e32 v124, v[124:125]
	v_mul_f32_e32 v123, v123, v0
	v_sin_f32_e32 v146, v124
	v_cos_f32_e32 v144, v124
	v_cvt_f64_f32_e32 v[124:125], v123
	v_mul_f64 v[138:139], v[124:125], s[84:85]
	v_rndne_f64_e32 v[138:139], v[138:139]
	v_fma_f64 v[124:125], v[124:125], s[84:85], -v[138:139]
	v_cvt_f32_f64_e32 v123, v[124:125]
	v_mul_f32_e32 v122, v122, v0
	v_sin_f32_e32 v155, v123
	v_cos_f32_e32 v143, v123
	v_cvt_f64_f32_e32 v[122:123], v122
	v_mul_f64 v[124:125], v[122:123], s[84:85]
	v_rndne_f64_e32 v[124:125], v[124:125]
	v_fma_f64 v[122:123], v[122:123], s[84:85], -v[124:125]
	v_cvt_f32_f64_e32 v122, v[122:123]
	v_sin_f32_e32 v154, v122
	v_cos_f32_e32 v142, v122
	v_mul_f32_e32 v122, v129, v0
	v_cvt_f64_f32_e32 v[122:123], v122
	v_mul_f64 v[124:125], v[122:123], s[84:85]
	v_rndne_f64_e32 v[124:125], v[124:125]
	v_fma_f64 v[122:123], v[122:123], s[84:85], -v[124:125]
	v_cvt_f32_f64_e32 v122, v[122:123]
	v_sin_f32_e32 v151, v122
	v_cos_f32_e32 v153, v122
	v_mul_f32_e32 v122, v128, v0
	v_cvt_f64_f32_e32 v[122:123], v122
	v_mul_f64 v[124:125], v[122:123], s[84:85]
	v_rndne_f64_e32 v[124:125], v[124:125]
	v_fma_f64 v[122:123], v[122:123], s[84:85], -v[124:125]
	v_cvt_f32_f64_e32 v122, v[122:123]
	v_sin_f32_e32 v150, v122
	v_cos_f32_e32 v152, v122
	v_mul_f32_e32 v122, v127, v0
	v_cvt_f64_f32_e32 v[122:123], v122
	v_mul_f64 v[124:125], v[122:123], s[84:85]
	v_rndne_f64_e32 v[124:125], v[124:125]
	v_fma_f64 v[122:123], v[122:123], s[84:85], -v[124:125]
	v_cvt_f32_f64_e32 v122, v[122:123]
	v_sin_f32_e32 v161, v122
	v_cos_f32_e32 v159, v122
	v_mul_f32_e32 v122, v126, v0
	v_cvt_f64_f32_e32 v[122:123], v122
	v_mul_f64 v[124:125], v[122:123], s[84:85]
	v_rndne_f64_e32 v[124:125], v[124:125]
	v_fma_f64 v[122:123], v[122:123], s[84:85], -v[124:125]
	v_cvt_f32_f64_e32 v122, v[122:123]
	v_sin_f32_e32 v160, v122
	v_cos_f32_e32 v158, v122
	v_mul_f32_e32 v122, v134, v0
	v_cvt_f64_f32_e32 v[122:123], v122
	v_mul_f64 v[124:125], v[122:123], s[84:85]
	v_rndne_f64_e32 v[124:125], v[124:125]
	v_fma_f64 v[122:123], v[122:123], s[84:85], -v[124:125]
	v_cvt_f32_f64_e32 v122, v[122:123]
	v_mul_f32_e32 v123, v135, v0
	v_cvt_f64_f32_e32 v[126:127], v123
	v_mul_f64 v[128:129], v[126:127], s[84:85]
	v_rndne_f64_e32 v[128:129], v[128:129]
	v_fma_f64 v[126:127], v[126:127], s[84:85], -v[128:129]
	v_cvt_f32_f64_e32 v123, v[126:127]
	v_mul_f32_e32 v126, v136, v0
	v_cvt_f64_f32_e32 v[126:127], v126
	v_mul_f64 v[128:129], v[126:127], s[84:85]
	v_rndne_f64_e32 v[128:129], v[128:129]
	v_fma_f64 v[126:127], v[126:127], s[84:85], -v[128:129]
	v_cvt_f32_f64_e32 v126, v[126:127]
	v_mul_f32_e32 v127, v137, v0
	v_cvt_f64_f32_e32 v[134:135], v127
	v_mul_f64 v[136:137], v[134:135], s[84:85]
	v_rndne_f64_e32 v[136:137], v[136:137]
	v_fma_f64 v[134:135], v[134:135], s[84:85], -v[136:137]
	v_mul_f32_e32 v130, v130, v0
	v_cvt_f32_f64_e32 v127, v[134:135]
	v_cvt_f64_f32_e32 v[134:135], v130
	v_mul_f64 v[136:137], v[134:135], s[84:85]
	v_rndne_f64_e32 v[136:137], v[136:137]
	v_mul_f32_e32 v130, v131, v0
	v_fma_f64 v[134:135], v[134:135], s[84:85], -v[136:137]
	v_cvt_f64_f32_e32 v[130:131], v130
	v_cvt_f32_f64_e32 v213, v[134:135]
	v_mul_f64 v[134:135], v[130:131], s[84:85]
	v_rndne_f64_e32 v[134:135], v[134:135]
	v_fma_f64 v[204:205], v[130:131], s[84:85], -v[134:135]
	v_mov_b32_e32 v130, v195
	v_mov_b32_e32 v131, v203
	v_mov_b32_e32 v121, v202
	v_pk_mul_f32 v[130:131], v[130:131], v[130:131]
	v_and_b32_e32 v199, 0xffff0000, v116
	v_lshlrev_b32_e32 v188, 16, v117
	v_pk_fma_f32 v[208:209], v[120:121], v[120:121], v[130:131]
	v_lshlrev_b32_e32 v198, 16, v116
	v_mov_b32_e32 v120, v189
	v_mov_b32_e32 v121, v199
	v_mov_b32_e32 v116, v188
	v_mov_b32_e32 v117, v198
	v_pk_mul_f32 v[120:121], v[120:121], v[120:121]
	v_and_b32_e32 v193, 0xffff0000, v115
	v_and_b32_e32 v201, 0xffff0000, v114
	v_pk_fma_f32 v[206:207], v[116:117], v[116:117], v[120:121]
	v_lshlrev_b32_e32 v192, 16, v115
	v_lshlrev_b32_e32 v200, 16, v114
	v_mov_b32_e32 v116, v193
	v_mov_b32_e32 v117, v201
	v_mov_b32_e32 v114, v192
	v_mov_b32_e32 v115, v200
	v_pk_mul_f32 v[116:117], v[116:117], v[116:117]
	v_mul_f32_e32 v230, v132, v0
	v_mul_f32_e32 v237, v133, v0
	v_pk_fma_f32 v[210:211], v[114:115], v[114:115], v[116:117]
	v_lshlrev_b32_e32 v136, 16, v113
	v_and_b32_e32 v137, 0xffff0000, v113
	v_lshlrev_b32_e32 v134, 16, v112
	v_and_b32_e32 v135, 0xffff0000, v112
	v_lshlrev_b32_e32 v138, 16, v111
	v_and_b32_e32 v139, 0xffff0000, v111
	v_lshlrev_b32_e32 v132, 16, v110
	v_and_b32_e32 v133, 0xffff0000, v110
	v_lshlrev_b32_e32 v140, 16, v109
	v_and_b32_e32 v141, 0xffff0000, v109
	v_lshlrev_b32_e32 v130, 16, v108
	v_and_b32_e32 v131, 0xffff0000, v108
	v_lshlrev_b32_e32 v156, 16, v106
	v_and_b32_e32 v157, 0xffff0000, v106
	v_lshlrev_b32_e32 v162, 16, v105
	v_and_b32_e32 v163, 0xffff0000, v105
	v_lshlrev_b32_e32 v164, 16, v104
	v_and_b32_e32 v165, 0xffff0000, v104
	v_lshlrev_b32_e32 v170, 16, v101
	v_and_b32_e32 v171, 0xffff0000, v101
	v_lshlrev_b32_e32 v186, 16, v95
	v_and_b32_e32 v187, 0xffff0000, v95
	v_lshlrev_b32_e32 v116, 16, v94
	v_and_b32_e32 v117, 0xffff0000, v94
	v_lshlrev_b32_e32 v94, 16, v93
	v_and_b32_e32 v95, 0xffff0000, v93
	v_lshlrev_b32_e32 v114, 16, v92
	v_and_b32_e32 v115, 0xffff0000, v92
	v_lshlrev_b32_e32 v92, 16, v91
	v_and_b32_e32 v93, 0xffff0000, v91
	v_lshlrev_b32_e32 v112, 16, v90
	v_and_b32_e32 v113, 0xffff0000, v90
	v_lshlrev_b32_e32 v90, 16, v89
	v_and_b32_e32 v91, 0xffff0000, v89
	v_lshlrev_b32_e32 v110, 16, v88
	v_and_b32_e32 v111, 0xffff0000, v88
	v_lshlrev_b32_e32 v88, 16, v87
	v_and_b32_e32 v89, 0xffff0000, v87
	v_lshlrev_b32_e32 v108, 16, v86
	v_and_b32_e32 v109, 0xffff0000, v86
	v_lshlrev_b32_e32 v86, 16, v85
	v_and_b32_e32 v87, 0xffff0000, v85
	v_lshlrev_b32_e32 v106, 16, v84
	v_and_b32_e32 v107, 0xffff0000, v84
	v_lshlrev_b32_e32 v84, 16, v83
	v_and_b32_e32 v85, 0xffff0000, v83
	v_lshlrev_b32_e32 v104, 16, v82
	v_and_b32_e32 v105, 0xffff0000, v82
	v_lshlrev_b32_e32 v82, 16, v81
	v_and_b32_e32 v83, 0xffff0000, v81
	v_and_b32_e32 v101, 0xffff0000, v77
	v_and_b32_e32 v81, 0xffff0000, v76
	v_lshlrev_b32_e32 v190, 16, v119
	v_and_b32_e32 v191, 0xffff0000, v119
	v_lshlrev_b32_e32 v196, 16, v118
	v_and_b32_e32 v197, 0xffff0000, v118
	v_lshlrev_b32_e32 v172, 16, v100
	v_and_b32_e32 v173, 0xffff0000, v100
	v_lshlrev_b32_e32 v174, 16, v99
	v_and_b32_e32 v175, 0xffff0000, v99
	v_lshlrev_b32_e32 v120, 16, v98
	v_and_b32_e32 v121, 0xffff0000, v98
	v_lshlrev_b32_e32 v184, 16, v97
	v_and_b32_e32 v185, 0xffff0000, v97
	v_lshlrev_b32_e32 v118, 16, v96
	v_and_b32_e32 v119, 0xffff0000, v96
	v_lshlrev_b32_e32 v100, 16, v77
	v_lshlrev_b32_e32 v98, 16, v80
	v_and_b32_e32 v99, 0xffff0000, v80
	v_lshlrev_b32_e32 v80, 16, v76
	v_mov_b32_e32 v96, v101
	v_mov_b32_e32 v97, v81
	v_mov_b32_e32 v76, v100
	v_mov_b32_e32 v77, v80
	v_pk_mul_f32 v[96:97], v[96:97], v[96:97]
	v_and_b32_e32 v179, 0xffff0000, v74
	v_pk_fma_f32 v[96:97], v[76:77], v[76:77], v[96:97]
	v_lshlrev_b32_e32 v76, 16, v79
	v_and_b32_e32 v77, 0xffff0000, v79
	v_and_b32_e32 v79, 0xffff0000, v75
	v_lshlrev_b32_e32 v166, 16, v103
	v_and_b32_e32 v167, 0xffff0000, v103
	v_lshlrev_b32_e32 v168, 16, v102
	v_and_b32_e32 v169, 0xffff0000, v102
	v_lshlrev_b32_e32 v102, 16, v78
	v_and_b32_e32 v103, 0xffff0000, v78
	v_lshlrev_b32_e32 v78, 16, v75
	v_lshlrev_b32_e32 v178, 16, v74
	v_mov_b32_e32 v218, v79
	v_mov_b32_e32 v219, v179
	v_pk_mul_f32 v[176:177], v[136:137], v[136:137]
	v_mov_b32_e32 v74, v78
	v_mov_b32_e32 v75, v178
	v_pk_mul_f32 v[218:219], v[218:219], v[218:219]
	v_add_f32_e32 v0, v176, v177
	v_pk_fma_f32 v[74:75], v[74:75], v[74:75], v[218:219]
	v_pk_mul_f32 v[218:219], v[138:139], v[138:139]
	v_pk_mul_f32 v[176:177], v[132:133], v[132:133]
	v_add_f32_e32 v218, v218, v219
	v_add_f32_e32 v219, v176, v177
	v_pk_mul_f32 v[176:177], v[134:135], v[134:135]
	v_add_f32_e32 v218, v219, v218
	v_add_f32_e32 v219, v176, v177
	v_add_f32_e32 v218, v219, v218
	v_add_f32_e32 v0, v0, v218
	v_pk_mul_f32 v[218:219], v[156:157], v[156:157]
	v_pk_mul_f32 v[176:177], v[190:191], v[190:191]
	v_add_f32_e32 v218, v218, v219
	v_add_f32_e32 v0, v218, v0
	v_pk_mul_f32 v[218:219], v[148:149], v[148:149]
	v_add_f32_e32 v176, v176, v177
	v_add_f32_e32 v218, v218, v219
	v_add_f32_e32 v0, v218, v0
	v_pk_mul_f32 v[218:219], v[130:131], v[130:131]
	v_mov_b32_e32 v238, v228
	v_add_f32_e32 v218, v218, v219
	v_add_f32_e32 v0, v218, v0
	v_pk_mul_f32 v[218:219], v[140:141], v[140:141]
	global_load_dwordx4 v[226:229], v212, s[24:25] offset:656
	v_add_f32_e32 v218, v218, v219
	v_add_f32_e32 v0, v218, v0
	v_pk_mul_f32 v[218:219], v[168:169], v[168:169]
	global_load_dwordx4 v[222:225], v212, s[24:25] offset:528
	v_add_f32_e32 v218, v218, v219
	v_add_f32_e32 v0, v218, v0
	v_pk_mul_f32 v[218:219], v[166:167], v[166:167]
	v_cvt_f32_f64_e32 v204, v[204:205]
	v_add_f32_e32 v218, v218, v219
	v_add_f32_e32 v0, v218, v0
	v_pk_mul_f32 v[218:219], v[164:165], v[164:165]
	v_cos_f32_e32 v235, v204
	v_add_f32_e32 v218, v218, v219
	v_add_f32_e32 v0, v218, v0
	v_pk_mul_f32 v[218:219], v[162:163], v[162:163]
	v_cos_f32_e32 v234, v213
	v_add_f32_e32 v218, v218, v219
	v_add_f32_e32 v0, v218, v0
	v_pk_mul_f32 v[218:219], v[120:121], v[120:121]
	v_sin_f32_e32 v124, v122
	v_add_f32_e32 v218, v218, v219
	v_add_f32_e32 v0, v218, v0
	v_pk_mul_f32 v[218:219], v[174:175], v[174:175]
	v_cos_f32_e32 v122, v122
	v_add_f32_e32 v218, v218, v219
	v_add_f32_e32 v0, v218, v0
	v_pk_mul_f32 v[218:219], v[172:173], v[172:173]
	v_sin_f32_e32 v125, v123
	v_add_f32_e32 v218, v218, v219
	v_add_f32_e32 v0, v218, v0
	v_pk_mul_f32 v[218:219], v[170:171], v[170:171]
	v_cos_f32_e32 v123, v123
	v_add_f32_e32 v218, v218, v219
	v_add_f32_e32 v0, v218, v0
	v_pk_mul_f32 v[218:219], v[116:117], v[116:117]
	v_sin_f32_e32 v128, v126
	v_add_f32_e32 v218, v218, v219
	v_add_f32_e32 v0, v218, v0
	v_pk_mul_f32 v[218:219], v[186:187], v[186:187]
	v_cos_f32_e32 v126, v126
	v_add_f32_e32 v218, v218, v219
	v_add_f32_e32 v0, v218, v0
	v_pk_mul_f32 v[218:219], v[118:119], v[118:119]
	v_sin_f32_e32 v129, v127
	v_add_f32_e32 v218, v218, v219
	v_add_f32_e32 v0, v218, v0
	v_pk_mul_f32 v[218:219], v[184:185], v[184:185]
	v_cos_f32_e32 v127, v127
	v_add_f32_e32 v218, v218, v219
	v_add_f32_e32 v0, v218, v0
	v_pk_mul_f32 v[218:219], v[112:113], v[112:113]
	s_lshl_b32 s28, s21, 2
	v_add_f32_e32 v218, v218, v219
	v_add_f32_e32 v0, v218, v0
	v_pk_mul_f32 v[218:219], v[92:93], v[92:93]
	s_ashr_i32 s21, s22, 7
	v_add_f32_e32 v218, v218, v219
	v_add_f32_e32 v0, v218, v0
	v_pk_mul_f32 v[218:219], v[114:115], v[114:115]
	s_mov_b32 s0, 0
	v_add_f32_e32 v218, v218, v219
	v_add_f32_e32 v0, v218, v0
	v_pk_mul_f32 v[218:219], v[94:95], v[94:95]
	s_mov_b32 s7, 2
	v_add_f32_e32 v218, v218, v219
	v_add_f32_e32 v0, v218, v0
	v_pk_mul_f32 v[218:219], v[108:109], v[108:109]
	s_add_i32 s21, s21, s28
	v_add_f32_e32 v218, v218, v219
	v_add_f32_e32 v0, v218, v0
	v_pk_mul_f32 v[218:219], v[88:89], v[88:89]
	s_add_i32 s28, s28, 4
	v_add_f32_e32 v218, v218, v219
	v_add_f32_e32 v0, v218, v0
	v_pk_mul_f32 v[218:219], v[110:111], v[110:111]
	s_movk_i32 s86, 0x80
	v_add_f32_e32 v218, v218, v219
	v_add_f32_e32 v0, v218, v0
	v_pk_mul_f32 v[218:219], v[90:91], v[90:91]
	s_mov_b32 s33, 0
	v_add_f32_e32 v218, v218, v219
	v_add_f32_e32 v0, v218, v0
	v_pk_mul_f32 v[218:219], v[104:105], v[104:105]
	s_nop 0
	v_add_f32_e32 v218, v218, v219
	v_add_f32_e32 v0, v218, v0
	v_pk_mul_f32 v[218:219], v[84:85], v[84:85]
	s_nop 0
	v_add_f32_e32 v218, v218, v219
	v_add_f32_e32 v0, v218, v0
	v_pk_mul_f32 v[218:219], v[106:107], v[106:107]
	s_nop 0
	v_add_f32_e32 v218, v218, v219
	v_add_f32_e32 v0, v218, v0
	v_pk_mul_f32 v[218:219], v[86:87], v[86:87]
	s_nop 0
	v_add_f32_e32 v218, v218, v219
	v_add_f32_e32 v0, v218, v0
	v_pk_mul_f32 v[218:219], v[102:103], v[102:103]
	s_nop 0
	v_add_f32_e32 v218, v218, v219
	v_add_f32_e32 v0, v218, v0
	v_pk_mul_f32 v[218:219], v[76:77], v[76:77]
	s_nop 0
	v_add_f32_e32 v218, v218, v219
	v_add_f32_e32 v0, v218, v0
	v_pk_mul_f32 v[218:219], v[98:99], v[98:99]
	s_nop 0
	v_add_f32_e32 v218, v218, v219
	v_add_f32_e32 v0, v218, v0
	v_pk_mul_f32 v[218:219], v[82:83], v[82:83]
	s_nop 0
	v_add_f32_e32 v218, v218, v219
	v_add_f32_e32 v0, v218, v0
	v_pk_mul_f32 v[218:219], v[196:197], v[196:197]
	s_nop 0
	v_add_f32_e32 v218, v218, v219
	v_add_f32_e32 v0, v218, v0
	v_add_f32_e32 v0, v176, v0
	v_add_f32_e32 v0, v209, v0
	v_add_f32_e32 v0, v208, v0
	v_add_f32_e32 v0, v75, v0
	v_add_f32_e32 v0, v74, v0
	v_add_f32_e32 v0, v97, v0
	v_add_f32_e32 v0, v96, v0
	v_add_f32_e32 v0, v211, v0
	v_add_f32_e32 v0, v210, v0
	v_add_f32_e32 v0, v207, v0
	v_add_f32_e32 v0, v206, v0
	ds_bpermute_b32 v177, v231, v0
	global_load_dwordx4 v[218:221], v212, s[24:25] offset:640
	v_cvt_f64_f32_e32 v[74:75], v230
	v_mul_f64 v[96:97], v[74:75], s[84:85]
	v_rndne_f64_e32 v[96:97], v[96:97]
	s_waitcnt lgkmcnt(0)
	v_add_f32_e32 v0, v0, v177
	v_fmamk_f32 v0, v0, 0x3baaaaab, v232
	v_fma_f64 v[74:75], v[74:75], s[84:85], -v[96:97]
	v_mul_f32_e32 v96, 0x4b800000, v0
	v_cmp_gt_f32_e32 vcc, s5, v0
	v_sin_f32_e32 v177, v204
	v_sin_f32_e32 v176, v213
	v_cndmask_b32_e32 v0, v0, v96, vcc
	v_rsq_f32_e32 v0, v0
	s_nop 0
	v_mul_f32_e32 v96, 0x45800000, v0
	v_cndmask_b32_e32 v0, v0, v96, vcc
	v_mul_f32_e32 v0, 0x3dd53b94, v0
	v_pk_mul_f32 v[96:97], v[0:1], v[194:195] op_sel_hi:[0,1]
	v_pk_mul_f32 v[72:73], v[72:73], v[96:97]
	v_pk_mul_f32 v[96:97], v[0:1], v[202:203] op_sel_hi:[0,1]
	global_load_dwordx4 v[202:205], v212, s[24:25] offset:464
	global_load_dwordx4 v[206:209], v212, s[24:25] offset:448
	v_pk_mul_f32 v[70:71], v[70:71], v[96:97]
	global_load_dwordx4 v[210:213], v212, s[24:25] offset:400
	v_cvt_f64_f32_e32 v[96:97], v237
	v_cvt_f32_f64_e32 v194, v[74:75]
	v_pk_mul_f32 v[74:75], v[0:1], v[188:189] op_sel_hi:[0,1]
	v_mul_f64 v[188:189], v[96:97], s[84:85]
	v_rndne_f64_e32 v[188:189], v[188:189]
	v_pk_mul_f32 v[68:69], v[68:69], v[74:75]
	v_pk_mul_f32 v[74:75], v[0:1], v[198:199] op_sel_hi:[0,1]
	v_fma_f64 v[96:97], v[96:97], s[84:85], -v[188:189]
	v_pk_mul_f32 v[66:67], v[66:67], v[74:75]
	v_cvt_f32_f64_e32 v96, v[96:97]
	v_sin_f32_e32 v75, v96
	v_cos_f32_e32 v189, v96
	v_pk_mul_f32 v[96:97], v[142:143], v[66:67]
	v_pk_mul_f32 v[66:67], v[154:155], v[66:67]
	v_sin_f32_e32 v74, v194
	v_cos_f32_e32 v188, v194
	v_pk_fma_f32 v[194:195], v[154:155], v[70:71], v[96:97]
	v_pk_fma_f32 v[66:67], v[142:143], v[70:71], v[66:67] neg_lo:[0,0,1] neg_hi:[0,0,1]
	v_pk_mul_f32 v[70:71], v[0:1], v[190:191] op_sel_hi:[0,1]
	v_pk_mul_f32 v[60:61], v[60:61], v[70:71]
	v_pk_mul_f32 v[70:71], v[0:1], v[192:193] op_sel_hi:[0,1]
	v_pk_mul_f32 v[64:65], v[64:65], v[70:71]
	v_pk_mul_f32 v[76:77], v[0:1], v[76:77] op_sel_hi:[0,1]
	v_pk_mul_f32 v[70:71], v[152:153], v[64:65]
	v_pk_mul_f32 v[64:65], v[150:151], v[64:65]
	v_pk_fma_f32 v[70:71], v[150:151], v[60:61], v[70:71]
	v_pk_fma_f32 v[60:61], v[152:153], v[60:61], v[64:65] neg_lo:[0,0,1] neg_hi:[0,0,1]
	v_pk_mul_f32 v[64:65], v[0:1], v[196:197] op_sel_hi:[0,1]
	v_pk_mul_f32 v[58:59], v[58:59], v[64:65]
	v_pk_mul_f32 v[64:65], v[0:1], v[200:201] op_sel_hi:[0,1]
	v_pk_mul_f32 v[62:63], v[62:63], v[64:65]
	v_pk_mul_f32 v[56:57], v[56:57], v[76:77]
	v_pk_mul_f32 v[64:65], v[158:159], v[62:63]
	v_pk_mul_f32 v[62:63], v[160:161], v[62:63]
	v_pk_fma_f32 v[64:65], v[160:161], v[58:59], v[64:65]
	v_pk_fma_f32 v[58:59], v[158:159], v[58:59], v[62:63] neg_lo:[0,0,1] neg_hi:[0,0,1]
	v_pk_mul_f32 v[62:63], v[0:1], v[102:103] op_sel_hi:[0,1]
	v_pk_mul_f32 v[54:55], v[54:55], v[62:63]
	v_pk_mul_f32 v[62:63], v[0:1], v[178:179] op_sel_hi:[0,1]
	v_pk_mul_f32 v[76:77], v[0:1], v[78:79] op_sel_hi:[0,1]
	v_pk_mul_f32 v[80:81], v[0:1], v[80:81] op_sel_hi:[0,1]
	v_pk_mul_f32 v[100:101], v[0:1], v[100:101] op_sel_hi:[0,1]
	s_waitcnt vmcnt(0)
	v_pk_mul_f32 v[80:81], v[226:227], v[80:81]
	v_pk_mul_f32 v[82:83], v[0:1], v[82:83] op_sel_hi:[0,1]
	v_pk_mul_f32 v[142:143], v[228:229], v[100:101]
	v_pk_mul_f32 v[82:83], v[224:225], v[82:83]
	v_pk_mul_f32 v[100:101], v[188:189], v[142:143]
	s_waitcnt vmcnt(5)
	s_barrier
	v_pk_fma_f32 v[100:101], v[74:75], v[82:83], v[100:101]
	v_mov_b32_e32 v228, v238
	v_pk_mul_f32 v[62:63], v[218:219], v[62:63]
	v_pk_mul_f32 v[76:77], v[220:221], v[76:77]
	v_pk_mul_f32 v[96:97], v[122:123], v[62:63]
	v_pk_mul_f32 v[78:79], v[126:127], v[76:77]
	v_pk_fma_f32 v[96:97], v[124:125], v[54:55], v[96:97]
	v_pk_fma_f32 v[78:79], v[128:129], v[56:57], v[78:79]
	v_cvt_pk_bf16_f32 v96, v96, v97
	v_cvt_pk_bf16_f32 v97, v78, v79
	v_pk_mul_f32 v[78:79], v[0:1], v[98:99] op_sel_hi:[0,1]
	v_pk_mul_f32 v[78:79], v[222:223], v[78:79]
	v_pk_mul_f32 v[98:99], v[234:235], v[80:81]
	v_pk_mul_f32 v[62:63], v[124:125], v[62:63]
	v_pk_fma_f32 v[98:99], v[176:177], v[78:79], v[98:99]
	v_pk_fma_f32 v[54:55], v[122:123], v[54:55], v[62:63] neg_lo:[0,0,1] neg_hi:[0,0,1]
	v_cvt_pk_bf16_f32 v98, v98, v99
	v_cvt_pk_bf16_f32 v99, v100, v101
	v_cvt_pk_bf16_f32 v100, v54, v55
	v_pk_mul_f32 v[54:55], v[128:129], v[76:77]
	v_mov_b32_e32 v218, 0
	v_pk_fma_f32 v[54:55], v[126:127], v[56:57], v[54:55] neg_lo:[0,0,1] neg_hi:[0,0,1]
	s_nop 0
	v_cvt_pk_bf16_f32 v101, v54, v55
	v_pk_mul_f32 v[54:55], v[176:177], v[80:81]
	s_nop 0
	v_pk_fma_f32 v[54:55], v[234:235], v[78:79], v[54:55] neg_lo:[0,0,1] neg_hi:[0,0,1]
	s_nop 0
	v_cvt_pk_bf16_f32 v102, v54, v55
	v_pk_mul_f32 v[54:55], v[74:75], v[142:143]
	v_cvt_pk_bf16_f32 v142, v66, v67
	v_pk_fma_f32 v[54:55], v[188:189], v[82:83], v[54:55] neg_lo:[0,0,1] neg_hi:[0,0,1]
	s_nop 0
	v_cvt_pk_bf16_f32 v103, v54, v55
	v_pk_mul_f32 v[54:55], v[0:1], v[104:105] op_sel_hi:[0,1]
	v_pk_mul_f32 v[54:55], v[206:207], v[54:55]
	s_nop 0
	v_cvt_pk_bf16_f32 v104, v54, v55
	v_pk_mul_f32 v[54:55], v[0:1], v[84:85] op_sel_hi:[0,1]
	v_pk_mul_f32 v[54:55], v[208:209], v[54:55]
	s_nop 0
	v_cvt_pk_bf16_f32 v105, v54, v55
	v_pk_mul_f32 v[54:55], v[0:1], v[106:107] op_sel_hi:[0,1]
	v_pk_mul_f32 v[54:55], v[202:203], v[54:55]
	s_nop 0
	v_cvt_pk_bf16_f32 v106, v54, v55
	v_pk_mul_f32 v[54:55], v[0:1], v[86:87] op_sel_hi:[0,1]
	v_pk_mul_f32 v[54:55], v[204:205], v[54:55]
	s_nop 0
	v_cvt_pk_bf16_f32 v107, v54, v55
	v_pk_mul_f32 v[54:55], v[0:1], v[108:109] op_sel_hi:[0,1]
	v_pk_mul_f32 v[50:51], v[50:51], v[54:55]
	s_nop 0
	v_cvt_pk_bf16_f32 v108, v50, v51
	v_pk_mul_f32 v[50:51], v[0:1], v[88:89] op_sel_hi:[0,1]
	v_pk_mul_f32 v[50:51], v[52:53], v[50:51]
	s_nop 0
	v_cvt_pk_bf16_f32 v109, v50, v51
	v_pk_mul_f32 v[50:51], v[0:1], v[110:111] op_sel_hi:[0,1]
	v_pk_mul_f32 v[50:51], v[210:211], v[50:51]
	s_nop 0
	v_cvt_pk_bf16_f32 v110, v50, v51
	v_pk_mul_f32 v[50:51], v[0:1], v[90:91] op_sel_hi:[0,1]
	v_pk_mul_f32 v[50:51], v[212:213], v[50:51]
	s_nop 0
	v_cvt_pk_bf16_f32 v111, v50, v51
	v_pk_mul_f32 v[50:51], v[0:1], v[112:113] op_sel_hi:[0,1]
	v_pk_mul_f32 v[46:47], v[46:47], v[50:51]
	s_nop 0
	v_cvt_pk_bf16_f32 v112, v46, v47
	v_pk_mul_f32 v[46:47], v[0:1], v[92:93] op_sel_hi:[0,1]
	v_pk_mul_f32 v[46:47], v[48:49], v[46:47]
	s_nop 0
	v_cvt_pk_bf16_f32 v113, v46, v47
	v_pk_mul_f32 v[46:47], v[0:1], v[114:115] op_sel_hi:[0,1]
	v_pk_mul_f32 v[42:43], v[42:43], v[46:47]
	s_nop 0
	v_cvt_pk_bf16_f32 v114, v42, v43
	v_pk_mul_f32 v[42:43], v[0:1], v[94:95] op_sel_hi:[0,1]
	v_pk_mul_f32 v[42:43], v[44:45], v[42:43]
	s_nop 0
	v_cvt_pk_bf16_f32 v115, v42, v43
	v_pk_mul_f32 v[42:43], v[0:1], v[116:117] op_sel_hi:[0,1]
	v_pk_mul_f32 v[38:39], v[38:39], v[42:43]
	s_nop 0
	v_cvt_pk_bf16_f32 v116, v38, v39
	v_pk_mul_f32 v[38:39], v[0:1], v[186:187] op_sel_hi:[0,1]
	v_pk_mul_f32 v[38:39], v[40:41], v[38:39]
	s_nop 0
	v_cvt_pk_bf16_f32 v117, v38, v39
	v_pk_mul_f32 v[38:39], v[0:1], v[118:119] op_sel_hi:[0,1]
	v_pk_mul_f32 v[34:35], v[34:35], v[38:39]
	s_nop 0
	v_cvt_pk_bf16_f32 v118, v34, v35
	v_pk_mul_f32 v[34:35], v[0:1], v[184:185] op_sel_hi:[0,1]
	v_pk_mul_f32 v[34:35], v[36:37], v[34:35]
	s_nop 0
	v_cvt_pk_bf16_f32 v119, v34, v35
	v_pk_mul_f32 v[34:35], v[0:1], v[120:121] op_sel_hi:[0,1]
	v_pk_mul_f32 v[30:31], v[30:31], v[34:35]
	s_nop 0
	v_cvt_pk_bf16_f32 v120, v30, v31
	v_pk_mul_f32 v[30:31], v[0:1], v[174:175] op_sel_hi:[0,1]
	v_pk_mul_f32 v[30:31], v[32:33], v[30:31]
	s_nop 0
	v_cvt_pk_bf16_f32 v121, v30, v31
	v_pk_mul_f32 v[30:31], v[0:1], v[172:173] op_sel_hi:[0,1]
	v_pk_mul_f32 v[26:27], v[26:27], v[30:31]
	s_nop 0
	v_cvt_pk_bf16_f32 v122, v26, v27
	v_pk_mul_f32 v[26:27], v[0:1], v[170:171] op_sel_hi:[0,1]
	v_pk_mul_f32 v[26:27], v[28:29], v[26:27]
	s_nop 0
	v_cvt_pk_bf16_f32 v123, v26, v27
	v_pk_mul_f32 v[26:27], v[0:1], v[168:169] op_sel_hi:[0,1]
	v_pk_mul_f32 v[22:23], v[22:23], v[26:27]
	s_nop 0
	v_cvt_pk_bf16_f32 v124, v22, v23
	v_pk_mul_f32 v[22:23], v[0:1], v[166:167] op_sel_hi:[0,1]
	v_pk_mul_f32 v[22:23], v[24:25], v[22:23]
	s_nop 0
	v_cvt_pk_bf16_f32 v125, v22, v23
	v_pk_mul_f32 v[22:23], v[0:1], v[164:165] op_sel_hi:[0,1]
	v_pk_mul_f32 v[18:19], v[18:19], v[22:23]
	s_nop 0
	v_cvt_pk_bf16_f32 v126, v18, v19
	v_pk_mul_f32 v[18:19], v[0:1], v[162:163] op_sel_hi:[0,1]
	v_pk_mul_f32 v[18:19], v[20:21], v[18:19]
	s_nop 0
	v_cvt_pk_bf16_f32 v127, v18, v19
	v_pk_mul_f32 v[18:19], v[0:1], v[156:157] op_sel_hi:[0,1]
	v_pk_mul_f32 v[14:15], v[14:15], v[18:19]
	s_nop 0
	v_cvt_pk_bf16_f32 v128, v14, v15
	v_pk_mul_f32 v[14:15], v[0:1], v[148:149] op_sel_hi:[0,1]
	v_pk_mul_f32 v[14:15], v[16:17], v[14:15]
	s_nop 0
	v_cvt_pk_bf16_f32 v129, v14, v15
	v_pk_mul_f32 v[14:15], v[0:1], v[130:131] op_sel_hi:[0,1]
	v_pk_mul_f32 v[10:11], v[10:11], v[14:15]
	v_mov_b32_e32 v14, v1
	v_cvt_pk_bf16_f32 v130, v10, v11
	v_pk_mul_f32 v[10:11], v[0:1], v[140:141] op_sel_hi:[0,1]
	v_pk_mul_f32 v[10:11], v[12:13], v[10:11]
	v_mov_b32_e32 v15, v1
	v_cvt_pk_bf16_f32 v131, v10, v11
	v_pk_mul_f32 v[10:11], v[0:1], v[132:133] op_sel_hi:[0,1]
	v_pk_mul_f32 v[6:7], v[6:7], v[10:11]
	v_cvt_pk_bf16_f32 v140, v58, v59
	v_cvt_pk_bf16_f32 v132, v6, v7
	v_pk_mul_f32 v[6:7], v[0:1], v[138:139] op_sel_hi:[0,1]
	v_pk_mul_f32 v[6:7], v[8:9], v[6:7]
	v_cvt_pk_bf16_f32 v141, v60, v61
	v_cvt_pk_bf16_f32 v133, v6, v7
	v_pk_mul_f32 v[6:7], v[0:1], v[134:135] op_sel_hi:[0,1]
	v_pk_mul_f32 v[2:3], v[2:3], v[6:7]
	v_mov_b32_e32 v6, v1
	v_cvt_pk_bf16_f32 v134, v2, v3
	v_pk_mul_f32 v[2:3], v[0:1], v[136:137] op_sel_hi:[0,1]
	v_pk_mul_f32 v[2:3], v[4:5], v[2:3]
	v_cvt_pk_bf16_f32 v136, v64, v65
	v_cvt_pk_bf16_f32 v135, v2, v3
	v_pk_mul_f32 v[2:3], v[144:145], v[68:69]
	v_cvt_pk_bf16_f32 v137, v70, v71
	v_pk_fma_f32 v[2:3], v[146:147], v[72:73], v[2:3]
	v_mov_b32_e32 v0, v1
	v_cvt_pk_bf16_f32 v139, v2, v3
	v_pk_mul_f32 v[2:3], v[146:147], v[68:69]
	v_mov_b32_e32 v4, v1
	v_pk_fma_f32 v[2:3], v[144:145], v[72:73], v[2:3] neg_lo:[0,0,1] neg_hi:[0,0,1]
	v_mov_b32_e32 v5, v1
	v_cvt_pk_bf16_f32 v143, v2, v3
	v_mov_b32_e32 v2, v1
	v_mov_b32_e32 v3, v1
	v_mov_b32_e32 v7, v1
	v_mov_b32_e32 v8, v1
	v_mov_b32_e32 v9, v1
	v_mov_b32_e32 v10, v1
	v_mov_b32_e32 v11, v1
	v_mov_b32_e32 v12, v1
	v_mov_b32_e32 v13, v1
	v_mov_b64_e32 v[30:31], v[14:15]
	v_mov_b64_e32 v[46:47], v[14:15]
	v_mov_b64_e32 v[62:63], v[14:15]
	v_mov_b64_e32 v[78:79], v[14:15]
	v_cvt_pk_bf16_f32 v138, v194, v195
	v_mov_b64_e32 v[28:29], v[12:13]
	v_mov_b64_e32 v[26:27], v[10:11]
	v_mov_b64_e32 v[24:25], v[8:9]
	v_mov_b64_e32 v[22:23], v[6:7]
	v_mov_b64_e32 v[20:21], v[4:5]
	v_mov_b64_e32 v[18:19], v[2:3]
	v_mov_b64_e32 v[16:17], v[0:1]
	v_mov_b64_e32 v[44:45], v[12:13]
	v_mov_b64_e32 v[42:43], v[10:11]
	v_mov_b64_e32 v[40:41], v[8:9]
	v_mov_b64_e32 v[38:39], v[6:7]
	v_mov_b64_e32 v[36:37], v[4:5]
	v_mov_b64_e32 v[34:35], v[2:3]
	v_mov_b64_e32 v[32:33], v[0:1]
	v_mov_b64_e32 v[60:61], v[12:13]
	v_mov_b64_e32 v[58:59], v[10:11]
	v_mov_b64_e32 v[56:57], v[8:9]
	v_mov_b64_e32 v[54:55], v[6:7]
	v_mov_b64_e32 v[52:53], v[4:5]
	v_mov_b64_e32 v[50:51], v[2:3]
	v_mov_b64_e32 v[48:49], v[0:1]
	v_mov_b64_e32 v[76:77], v[12:13]
	v_mov_b64_e32 v[74:75], v[10:11]
	v_mov_b64_e32 v[72:73], v[8:9]
	v_mov_b64_e32 v[70:71], v[6:7]
	v_mov_b64_e32 v[68:69], v[4:5]
	v_mov_b64_e32 v[66:67], v[2:3]
	v_mov_b64_e32 v[64:65], v[0:1]
	v_mov_b32_e32 v206, v217
	v_lshlrev_b32_e32 v209, 3, v206
	v_lshrrev_b32_e32 v207, 1, v206
	v_lshlrev_b32_e32 v208, 7, v206
	v_and_b32_e32 v209, 8, v209
	v_ashrrev_i32_e32 v206, 5, v206
	v_add_u32_e32 v206, v209, v206
	v_and_b32_e32 v208, 0xf00, v208
	v_bitop3_b32 v209, v206, v207, 7 bitop3:0x78
	v_add_u32_e32 v210, 2, v206
	v_add_u32_e32 v211, 4, v206
	v_add_u32_e32 v206, 6, v206
	v_bitop3_b32 v210, v210, v207, 7 bitop3:0x78
	v_bitop3_b32 v211, v211, v207, 7 bitop3:0x78
	v_bitop3_b32 v206, v206, v207, 7 bitop3:0x78
	v_lshl_add_u32 v0, v209, 4, v208
	v_lshl_add_u32 v212, v210, 4, v208
	v_lshl_add_u32 v213, v211, 4, v208
	v_lshl_add_u32 v219, v206, 4, v208
	s_mov_b32 s100, 0
	s_branch .LBB0_531

.LBB0_531:
	s_add_i32 s10, s33, 2
	s_cmp_ge_u32 s10, s28
	s_cselect_b64 s[22:23], -1, 0
	s_mov_b64 s[34:35], -1
	s_cmp_gt_i32 s33, s21
	s_cbranch_scc1 .Lat1_skip
	s_and_b64 vcc, exec, s[22:23]
	s_cbranch_vccnz .Lat1_nodma
	s_setprio 3
	s_mul_i32 s10, s0, 0xa000
	v_add_u32_e32 v14, s10, v0
	v_add_u32_e32 v15, s10, v212
	v_add_u32_e32 v176, s10, v213
	v_add_u32_e32 v177, s10, v219
	ds_read_b128 v[144:147], v14 offset:0
	ds_read_b128 v[148:151], v15 offset:0
	ds_read_b128 v[152:155], v176 offset:0
	ds_read_b128 v[156:159], v177 offset:0
	ds_read_b128 v[160:163], v14 offset:8192
	ds_read_b128 v[164:167], v15 offset:8192
	ds_read_b128 v[168:171], v176 offset:8192
	ds_read_b128 v[172:175], v177 offset:8192
	ds_read_b128 v[2:5], v14 offset:16384
	ds_read_b128 v[6:9], v15 offset:16384
	ds_read_b128 v[10:13], v176 offset:16384
	ds_read_b128 v[238:241], v177 offset:16384
	s_cmp_eq_u32 s100, 0
	s_cbranch_scc1 .Lat1_nopend1
	v_mfma_f32_32x32x16_bf16 v[64:79], v[188:191], v[220:223], v[64:79]
	v_mfma_f32_32x32x16_bf16 v[48:63], v[188:191], v[224:227], v[48:63]
	v_mfma_f32_32x32x16_bf16 v[32:47], v[188:191], v[242:245], v[32:47]
	v_mfma_f32_32x32x16_bf16 v[16:31], v[188:191], v[246:249], v[16:31]
.Lat1_nopend1:
	v_mad_u64_u32 v[202:203], s[10:11], s86, v228, v[180:181]
	s_mul_i32 s10, s7, 0xa000
	s_add_i32 s10, s9, s10
	s_mov_b32 m0, s10
	v_lshl_add_u64 v[204:205], v[202:203], 0, s[94:95]
	global_load_lds_dwordx4 v[202:203], off
	s_add_i32 m0, s10, 0x2000
	v_lshl_add_u64 v[202:203], v[202:203], 0, s[96:97]
	global_load_lds_dwordx4 v[204:205], off
	s_waitcnt lgkmcnt(8)
	v_mfma_f32_32x32x16_bf16 v[80:95], v[144:147], v[132:135], 0
	s_add_i32 m0, s10, 0x4000
	v_mfma_f32_32x32x16_bf16 v[80:95], v[148:151], v[128:131], v[80:95]
	global_load_lds_dwordx4 v[202:203], off
	v_lshl_add_u64 v[202:203], s[86:87], 1, v[182:183]
	s_add_i32 m0, s10, 0x6000
	v_mfma_f32_32x32x16_bf16 v[80:95], v[152:155], v[124:127], v[80:95]
	global_load_lds_dwordx4 v[202:203], off
	v_lshl_add_u64 v[202:203], v[202:203], 0, s[92:93]
	s_add_i32 m0, s10, 0x8000
	v_mfma_f32_32x32x16_bf16 v[80:95], v[156:159], v[120:123], v[80:95]
	global_load_lds_dwordx4 v[202:203], off
	ds_read_b128 v[144:147], v14 offset:4096
	ds_read_b128 v[148:151], v15 offset:4096
	ds_read_b128 v[152:155], v176 offset:4096
	ds_read_b128 v[156:159], v177 offset:4096
	s_waitcnt lgkmcnt(8)
	v_mfma_f32_32x32x16_bf16 v[80:95], v[160:163], v[116:119], v[80:95]
	v_mfma_f32_32x32x16_bf16 v[80:95], v[164:167], v[112:115], v[80:95]
	v_mfma_f32_32x32x16_bf16 v[80:95], v[168:171], v[108:111], v[80:95]
	v_mfma_f32_32x32x16_bf16 v[80:95], v[172:175], v[104:107], v[80:95]
	ds_read_b128 v[160:163], v14 offset:12288
	ds_read_b128 v[164:167], v15 offset:12288
	ds_read_b128 v[168:171], v176 offset:12288
	ds_read_b128 v[172:175], v177 offset:12288
	s_waitcnt lgkmcnt(8)
	v_mfma_f32_32x32x16_bf16 v[80:95], v[2:5], v[100:103], v[80:95]
	v_mfma_f32_32x32x16_bf16 v[80:95], v[6:9], v[140:143], v[80:95]
	v_mfma_f32_32x32x16_bf16 v[80:95], v[10:13], v[96:99], v[80:95]
	v_mfma_f32_32x32x16_bf16 v[80:95], v[238:241], v[136:139], v[80:95]
	s_setprio 2
	ds_read_b128 v[2:5], v14 offset:20480
	ds_read_b128 v[6:9], v15 offset:20480
	ds_read_b128 v[10:13], v176 offset:20480
	ds_read_b128 v[238:241], v177 offset:20480
	s_waitcnt lgkmcnt(8)
	v_mfma_f32_32x32x16_bf16 v[184:199], v[144:147], v[132:135], 0
	v_mfma_f32_32x32x16_bf16 v[184:199], v[148:151], v[128:131], v[184:199]
	v_mfma_f32_32x32x16_bf16 v[184:199], v[152:155], v[124:127], v[184:199]
	v_mfma_f32_32x32x16_bf16 v[184:199], v[156:159], v[120:123], v[184:199]
	ds_read_b128 v[144:147], v14 offset:24576
	ds_read_b128 v[148:151], v14 offset:28672
	ds_read_b128 v[152:155], v14 offset:32768
	ds_read_b128 v[156:159], v14 offset:36864
	s_waitcnt lgkmcnt(8)
	v_mfma_f32_32x32x16_bf16 v[184:199], v[160:163], v[116:119], v[184:199]
	v_med3_f32 v80, v80, s4, v236
	v_exp_f32_e32 v80, v80
	v_med3_f32 v81, v81, s4, v236
	v_exp_f32_e32 v81, v81
	v_mfma_f32_32x32x16_bf16 v[184:199], v[164:167], v[112:115], v[184:199]
	v_med3_f32 v82, v82, s4, v236
	v_exp_f32_e32 v82, v82
	v_med3_f32 v83, v83, s4, v236
	v_exp_f32_e32 v83, v83
	v_mfma_f32_32x32x16_bf16 v[184:199], v[168:171], v[108:111], v[184:199]
	v_med3_f32 v84, v84, s4, v236
	v_exp_f32_e32 v84, v84
	v_med3_f32 v85, v85, s4, v236
	v_exp_f32_e32 v85, v85
	v_mfma_f32_32x32x16_bf16 v[184:199], v[172:175], v[104:107], v[184:199]
	v_med3_f32 v86, v86, s4, v236
	v_exp_f32_e32 v86, v86
	v_med3_f32 v87, v87, s4, v236
	v_exp_f32_e32 v87, v87
	ds_read_b128 v[160:163], v15 offset:24576
	ds_read_b128 v[164:167], v15 offset:28672
	ds_read_b128 v[168:171], v15 offset:32768
	ds_read_b128 v[172:175], v15 offset:36864
	s_waitcnt lgkmcnt(8)
	v_mfma_f32_32x32x16_bf16 v[184:199], v[2:5], v[100:103], v[184:199]
	v_med3_f32 v88, v88, s4, v236
	v_exp_f32_e32 v88, v88
	v_med3_f32 v89, v89, s4, v236
	v_exp_f32_e32 v89, v89
	v_add_f32_e32 v200, v80, v81
	v_add_f32_e32 v200, v200, v82
	v_mfma_f32_32x32x16_bf16 v[184:199], v[6:9], v[140:143], v[184:199]
	v_med3_f32 v90, v90, s4, v236
	v_exp_f32_e32 v90, v90
	v_med3_f32 v91, v91, s4, v236
	v_exp_f32_e32 v91, v91
	v_add_f32_e32 v200, v200, v83
	v_add_f32_e32 v200, v200, v84
	v_mfma_f32_32x32x16_bf16 v[184:199], v[10:13], v[96:99], v[184:199]
	v_med3_f32 v92, v92, s4, v236
	v_exp_f32_e32 v92, v92
	v_med3_f32 v93, v93, s4, v236
	v_exp_f32_e32 v93, v93
	v_add_f32_e32 v200, v200, v85
	v_add_f32_e32 v200, v200, v86
	v_mfma_f32_32x32x16_bf16 v[184:199], v[238:241], v[136:139], v[184:199]
	v_med3_f32 v94, v94, s4, v236
	v_exp_f32_e32 v94, v94
	v_med3_f32 v95, v95, s4, v236
	v_exp_f32_e32 v95, v95
	v_add_f32_e32 v200, v200, v87
	s_setprio 1
	ds_read_b128 v[2:5], v176 offset:24576
	ds_read_b128 v[6:9], v176 offset:28672
	ds_read_b128 v[10:13], v176 offset:32768
	ds_read_b128 v[238:241], v176 offset:36864
	v_cvt_pk_bf16_f32 v80, v80, v81
	v_cvt_pk_bf16_f32 v81, v82, v83
	v_cvt_pk_bf16_f32 v82, v84, v85
	v_cvt_pk_bf16_f32 v83, v86, v87
	v_add_f32_e32 v200, v200, v88
	v_add_f32_e32 v200, v200, v89
	s_waitcnt lgkmcnt(8)
	v_mfma_f32_32x32x16_bf16 v[64:79], v[80:83], v[144:147], v[64:79]
	v_med3_f32 v184, v184, s4, v236
	v_exp_f32_e32 v184, v184
	v_med3_f32 v185, v185, s4, v236
	v_exp_f32_e32 v185, v185
	v_add_f32_e32 v200, v200, v90
	v_add_f32_e32 v200, v200, v91
	v_mfma_f32_32x32x16_bf16 v[48:63], v[80:83], v[148:151], v[48:63]
	v_med3_f32 v186, v186, s4, v236
	v_exp_f32_e32 v186, v186
	v_med3_f32 v187, v187, s4, v236
	v_exp_f32_e32 v187, v187
	v_add_f32_e32 v200, v200, v92
	v_add_f32_e32 v200, v200, v93
	v_mfma_f32_32x32x16_bf16 v[32:47], v[80:83], v[152:155], v[32:47]
	v_med3_f32 v188, v188, s4, v236
	v_exp_f32_e32 v188, v188
	v_med3_f32 v189, v189, s4, v236
	v_exp_f32_e32 v189, v189
	v_add_f32_e32 v200, v200, v94
	v_add_f32_e32 v200, v200, v95
	v_mfma_f32_32x32x16_bf16 v[16:31], v[80:83], v[156:159], v[16:31]
	v_med3_f32 v190, v190, s4, v236
	v_exp_f32_e32 v190, v190
	v_med3_f32 v191, v191, s4, v236
	v_exp_f32_e32 v191, v191
	v_cvt_pk_bf16_f32 v84, v88, v89
	v_cvt_pk_bf16_f32 v85, v90, v91
	v_cvt_pk_bf16_f32 v86, v92, v93
	v_cvt_pk_bf16_f32 v87, v94, v95
	ds_read_b128 v[220:223], v177 offset:24576
	ds_read_b128 v[224:227], v177 offset:28672
	ds_read_b128 v[242:245], v177 offset:32768
	ds_read_b128 v[246:249], v177 offset:36864
	s_waitcnt lgkmcnt(8)
	v_mfma_f32_32x32x16_bf16 v[64:79], v[84:87], v[160:163], v[64:79]
	v_med3_f32 v192, v192, s4, v236
	v_exp_f32_e32 v192, v192
	v_med3_f32 v193, v193, s4, v236
	v_exp_f32_e32 v193, v193
	v_add_f32_e32 v201, v184, v185
	v_add_f32_e32 v201, v201, v186
	v_mfma_f32_32x32x16_bf16 v[48:63], v[84:87], v[164:167], v[48:63]
	v_med3_f32 v194, v194, s4, v236
	v_exp_f32_e32 v194, v194
	v_med3_f32 v195, v195, s4, v236
	v_exp_f32_e32 v195, v195
	v_add_f32_e32 v201, v201, v187
	v_add_f32_e32 v201, v201, v188
	v_mfma_f32_32x32x16_bf16 v[32:47], v[84:87], v[168:171], v[32:47]
	v_med3_f32 v196, v196, s4, v236
	v_exp_f32_e32 v196, v196
	v_med3_f32 v197, v197, s4, v236
	v_exp_f32_e32 v197, v197
	v_add_f32_e32 v201, v201, v189
	v_mfma_f32_32x32x16_bf16 v[16:31], v[84:87], v[172:175], v[16:31]
	v_med3_f32 v198, v198, s4, v236
	v_exp_f32_e32 v198, v198
	v_med3_f32 v199, v199, s4, v236
	v_exp_f32_e32 v199, v199
	v_add_f32_e32 v201, v201, v190
	v_cvt_pk_bf16_f32 v184, v184, v185
	v_cvt_pk_bf16_f32 v185, v186, v187
	v_cvt_pk_bf16_f32 v186, v188, v189
	v_cvt_pk_bf16_f32 v187, v190, v191
	v_add_f32_e32 v201, v201, v191
	s_setprio 0
	s_waitcnt lgkmcnt(4)
	v_mfma_f32_32x32x16_bf16 v[64:79], v[184:187], v[2:5], v[64:79]
	v_add_f32_e32 v201, v201, v192
	v_add_f32_e32 v201, v201, v193
	v_add_f32_e32 v201, v201, v194
	v_mfma_f32_32x32x16_bf16 v[48:63], v[184:187], v[6:9], v[48:63]
	v_add_f32_e32 v201, v201, v195
	v_add_f32_e32 v201, v201, v196
	v_add_f32_e32 v201, v201, v197
	v_mfma_f32_32x32x16_bf16 v[32:47], v[184:187], v[10:13], v[32:47]
	v_add_f32_e32 v201, v201, v198
	v_add_f32_e32 v201, v201, v199
	v_cvt_pk_bf16_f32 v188, v192, v193
	v_cvt_pk_bf16_f32 v189, v194, v195
	v_cvt_pk_bf16_f32 v190, v196, v197
	v_cvt_pk_bf16_f32 v191, v198, v199
	v_mfma_f32_32x32x16_bf16 v[16:31], v[184:187], v[238:241], v[16:31]
	v_add_f32_e32 v200, v200, v201
	v_add_f32_e32 v218, v218, v200
	s_mov_b32 s100, 1
	s_waitcnt vmcnt(5) lgkmcnt(0)
	s_branch .LBB0_530
.Lat1_nodma:
	s_setprio 3
	s_mul_i32 s10, s0, 0xa000
	v_add_u32_e32 v14, s10, v0
	v_add_u32_e32 v15, s10, v212
	v_add_u32_e32 v176, s10, v213
	v_add_u32_e32 v177, s10, v219
	ds_read_b128 v[144:147], v14 offset:0
	ds_read_b128 v[148:151], v15 offset:0
	ds_read_b128 v[152:155], v176 offset:0
	ds_read_b128 v[156:159], v177 offset:0
	ds_read_b128 v[160:163], v14 offset:8192
	ds_read_b128 v[164:167], v15 offset:8192
	ds_read_b128 v[168:171], v176 offset:8192
	ds_read_b128 v[172:175], v177 offset:8192
	ds_read_b128 v[2:5], v14 offset:16384
	ds_read_b128 v[6:9], v15 offset:16384
	ds_read_b128 v[10:13], v176 offset:16384
	ds_read_b128 v[238:241], v177 offset:16384
	s_cmp_eq_u32 s100, 0
	s_cbranch_scc1 .Lat1_nopend2
	v_mfma_f32_32x32x16_bf16 v[64:79], v[188:191], v[220:223], v[64:79]
	v_mfma_f32_32x32x16_bf16 v[48:63], v[188:191], v[224:227], v[48:63]
	v_mfma_f32_32x32x16_bf16 v[32:47], v[188:191], v[242:245], v[32:47]
	v_mfma_f32_32x32x16_bf16 v[16:31], v[188:191], v[246:249], v[16:31]
.Lat1_nopend2:
	s_waitcnt lgkmcnt(8)
	v_mfma_f32_32x32x16_bf16 v[80:95], v[144:147], v[132:135], 0
	v_mfma_f32_32x32x16_bf16 v[80:95], v[148:151], v[128:131], v[80:95]
	v_mfma_f32_32x32x16_bf16 v[80:95], v[152:155], v[124:127], v[80:95]
	v_mfma_f32_32x32x16_bf16 v[80:95], v[156:159], v[120:123], v[80:95]
	ds_read_b128 v[144:147], v14 offset:4096
	ds_read_b128 v[148:151], v15 offset:4096
	ds_read_b128 v[152:155], v176 offset:4096
	ds_read_b128 v[156:159], v177 offset:4096
	s_waitcnt lgkmcnt(8)
	v_mfma_f32_32x32x16_bf16 v[80:95], v[160:163], v[116:119], v[80:95]
	v_mfma_f32_32x32x16_bf16 v[80:95], v[164:167], v[112:115], v[80:95]
	v_mfma_f32_32x32x16_bf16 v[80:95], v[168:171], v[108:111], v[80:95]
	v_mfma_f32_32x32x16_bf16 v[80:95], v[172:175], v[104:107], v[80:95]
	ds_read_b128 v[160:163], v14 offset:12288
	ds_read_b128 v[164:167], v15 offset:12288
	ds_read_b128 v[168:171], v176 offset:12288
	ds_read_b128 v[172:175], v177 offset:12288
	s_waitcnt lgkmcnt(8)
	v_mfma_f32_32x32x16_bf16 v[80:95], v[2:5], v[100:103], v[80:95]
	v_mfma_f32_32x32x16_bf16 v[80:95], v[6:9], v[140:143], v[80:95]
	v_mfma_f32_32x32x16_bf16 v[80:95], v[10:13], v[96:99], v[80:95]
	v_mfma_f32_32x32x16_bf16 v[80:95], v[238:241], v[136:139], v[80:95]
	s_setprio 2
	ds_read_b128 v[2:5], v14 offset:20480
	ds_read_b128 v[6:9], v15 offset:20480
	ds_read_b128 v[10:13], v176 offset:20480
	ds_read_b128 v[238:241], v177 offset:20480
	s_waitcnt lgkmcnt(8)
	v_mfma_f32_32x32x16_bf16 v[184:199], v[144:147], v[132:135], 0
	v_mfma_f32_32x32x16_bf16 v[184:199], v[148:151], v[128:131], v[184:199]
	v_mfma_f32_32x32x16_bf16 v[184:199], v[152:155], v[124:127], v[184:199]
	v_mfma_f32_32x32x16_bf16 v[184:199], v[156:159], v[120:123], v[184:199]
	ds_read_b128 v[144:147], v14 offset:24576
	ds_read_b128 v[148:151], v14 offset:28672
	ds_read_b128 v[152:155], v14 offset:32768
	ds_read_b128 v[156:159], v14 offset:36864
	s_waitcnt lgkmcnt(8)
	v_mfma_f32_32x32x16_bf16 v[184:199], v[160:163], v[116:119], v[184:199]
	v_med3_f32 v80, v80, s4, v236
	v_exp_f32_e32 v80, v80
	v_med3_f32 v81, v81, s4, v236
	v_exp_f32_e32 v81, v81
	v_mfma_f32_32x32x16_bf16 v[184:199], v[164:167], v[112:115], v[184:199]
	v_med3_f32 v82, v82, s4, v236
	v_exp_f32_e32 v82, v82
	v_med3_f32 v83, v83, s4, v236
	v_exp_f32_e32 v83, v83
	v_mfma_f32_32x32x16_bf16 v[184:199], v[168:171], v[108:111], v[184:199]
	v_med3_f32 v84, v84, s4, v236
	v_exp_f32_e32 v84, v84
	v_med3_f32 v85, v85, s4, v236
	v_exp_f32_e32 v85, v85
	v_mfma_f32_32x32x16_bf16 v[184:199], v[172:175], v[104:107], v[184:199]
	v_med3_f32 v86, v86, s4, v236
	v_exp_f32_e32 v86, v86
	v_med3_f32 v87, v87, s4, v236
	v_exp_f32_e32 v87, v87
	ds_read_b128 v[160:163], v15 offset:24576
	ds_read_b128 v[164:167], v15 offset:28672
	ds_read_b128 v[168:171], v15 offset:32768
	ds_read_b128 v[172:175], v15 offset:36864
	s_waitcnt lgkmcnt(8)
	v_mfma_f32_32x32x16_bf16 v[184:199], v[2:5], v[100:103], v[184:199]
	v_med3_f32 v88, v88, s4, v236
	v_exp_f32_e32 v88, v88
	v_med3_f32 v89, v89, s4, v236
	v_exp_f32_e32 v89, v89
	v_add_f32_e32 v200, v80, v81
	v_add_f32_e32 v200, v200, v82
	v_mfma_f32_32x32x16_bf16 v[184:199], v[6:9], v[140:143], v[184:199]
	v_med3_f32 v90, v90, s4, v236
	v_exp_f32_e32 v90, v90
	v_med3_f32 v91, v91, s4, v236
	v_exp_f32_e32 v91, v91
	v_add_f32_e32 v200, v200, v83
	v_add_f32_e32 v200, v200, v84
	v_mfma_f32_32x32x16_bf16 v[184:199], v[10:13], v[96:99], v[184:199]
	v_med3_f32 v92, v92, s4, v236
	v_exp_f32_e32 v92, v92
	v_med3_f32 v93, v93, s4, v236
	v_exp_f32_e32 v93, v93
	v_add_f32_e32 v200, v200, v85
	v_add_f32_e32 v200, v200, v86
	v_mfma_f32_32x32x16_bf16 v[184:199], v[238:241], v[136:139], v[184:199]
	v_med3_f32 v94, v94, s4, v236
	v_exp_f32_e32 v94, v94
	v_med3_f32 v95, v95, s4, v236
	v_exp_f32_e32 v95, v95
	v_add_f32_e32 v200, v200, v87
	s_setprio 1
	ds_read_b128 v[2:5], v176 offset:24576
	ds_read_b128 v[6:9], v176 offset:28672
	ds_read_b128 v[10:13], v176 offset:32768
	ds_read_b128 v[238:241], v176 offset:36864
	v_cvt_pk_bf16_f32 v80, v80, v81
	v_cvt_pk_bf16_f32 v81, v82, v83
	v_cvt_pk_bf16_f32 v82, v84, v85
	v_cvt_pk_bf16_f32 v83, v86, v87
	v_add_f32_e32 v200, v200, v88
	v_add_f32_e32 v200, v200, v89
	s_waitcnt lgkmcnt(8)
	v_mfma_f32_32x32x16_bf16 v[64:79], v[80:83], v[144:147], v[64:79]
	v_med3_f32 v184, v184, s4, v236
	v_exp_f32_e32 v184, v184
	v_med3_f32 v185, v185, s4, v236
	v_exp_f32_e32 v185, v185
	v_add_f32_e32 v200, v200, v90
	v_add_f32_e32 v200, v200, v91
	v_mfma_f32_32x32x16_bf16 v[48:63], v[80:83], v[148:151], v[48:63]
	v_med3_f32 v186, v186, s4, v236
	v_exp_f32_e32 v186, v186
	v_med3_f32 v187, v187, s4, v236
	v_exp_f32_e32 v187, v187
	v_add_f32_e32 v200, v200, v92
	v_add_f32_e32 v200, v200, v93
	v_mfma_f32_32x32x16_bf16 v[32:47], v[80:83], v[152:155], v[32:47]
	v_med3_f32 v188, v188, s4, v236
	v_exp_f32_e32 v188, v188
	v_med3_f32 v189, v189, s4, v236
	v_exp_f32_e32 v189, v189
	v_add_f32_e32 v200, v200, v94
	v_add_f32_e32 v200, v200, v95
	v_mfma_f32_32x32x16_bf16 v[16:31], v[80:83], v[156:159], v[16:31]
	v_med3_f32 v190, v190, s4, v236
	v_exp_f32_e32 v190, v190
	v_med3_f32 v191, v191, s4, v236
	v_exp_f32_e32 v191, v191
	v_cvt_pk_bf16_f32 v84, v88, v89
	v_cvt_pk_bf16_f32 v85, v90, v91
	v_cvt_pk_bf16_f32 v86, v92, v93
	v_cvt_pk_bf16_f32 v87, v94, v95
	ds_read_b128 v[220:223], v177 offset:24576
	ds_read_b128 v[224:227], v177 offset:28672
	ds_read_b128 v[242:245], v177 offset:32768
	ds_read_b128 v[246:249], v177 offset:36864
	s_waitcnt lgkmcnt(8)
	v_mfma_f32_32x32x16_bf16 v[64:79], v[84:87], v[160:163], v[64:79]
	v_med3_f32 v192, v192, s4, v236
	v_exp_f32_e32 v192, v192
	v_med3_f32 v193, v193, s4, v236
	v_exp_f32_e32 v193, v193
	v_add_f32_e32 v201, v184, v185
	v_add_f32_e32 v201, v201, v186
	v_mfma_f32_32x32x16_bf16 v[48:63], v[84:87], v[164:167], v[48:63]
	v_med3_f32 v194, v194, s4, v236
	v_exp_f32_e32 v194, v194
	v_med3_f32 v195, v195, s4, v236
	v_exp_f32_e32 v195, v195
	v_add_f32_e32 v201, v201, v187
	v_add_f32_e32 v201, v201, v188
	v_mfma_f32_32x32x16_bf16 v[32:47], v[84:87], v[168:171], v[32:47]
	v_med3_f32 v196, v196, s4, v236
	v_exp_f32_e32 v196, v196
	v_med3_f32 v197, v197, s4, v236
	v_exp_f32_e32 v197, v197
	v_add_f32_e32 v201, v201, v189
	v_mfma_f32_32x32x16_bf16 v[16:31], v[84:87], v[172:175], v[16:31]
	v_med3_f32 v198, v198, s4, v236
	v_exp_f32_e32 v198, v198
	v_med3_f32 v199, v199, s4, v236
	v_exp_f32_e32 v199, v199
	v_add_f32_e32 v201, v201, v190
	v_cvt_pk_bf16_f32 v184, v184, v185
	v_cvt_pk_bf16_f32 v185, v186, v187
	v_cvt_pk_bf16_f32 v186, v188, v189
	v_cvt_pk_bf16_f32 v187, v190, v191
	v_add_f32_e32 v201, v201, v191
	s_setprio 0
	s_waitcnt lgkmcnt(4)
	v_mfma_f32_32x32x16_bf16 v[64:79], v[184:187], v[2:5], v[64:79]
	v_add_f32_e32 v201, v201, v192
	v_add_f32_e32 v201, v201, v193
	v_add_f32_e32 v201, v201, v194
	v_mfma_f32_32x32x16_bf16 v[48:63], v[184:187], v[6:9], v[48:63]
	v_add_f32_e32 v201, v201, v195
	v_add_f32_e32 v201, v201, v196
	v_add_f32_e32 v201, v201, v197
	v_mfma_f32_32x32x16_bf16 v[32:47], v[184:187], v[10:13], v[32:47]
	v_add_f32_e32 v201, v201, v198
	v_add_f32_e32 v201, v201, v199
	v_cvt_pk_bf16_f32 v188, v192, v193
	v_cvt_pk_bf16_f32 v189, v194, v195
	v_cvt_pk_bf16_f32 v190, v196, v197
	v_cvt_pk_bf16_f32 v191, v198, v199
	v_mfma_f32_32x32x16_bf16 v[16:31], v[184:187], v[238:241], v[16:31]
	v_add_f32_e32 v200, v200, v201
	v_add_f32_e32 v218, v218, v200
	s_mov_b32 s100, 1
	s_waitcnt vmcnt(0) lgkmcnt(0)
	s_branch .LBB0_530

.LBB0_539:
	s_cmp_eq_u32 s100, 0
	s_cbranch_scc1 .Lat1_noflush
	v_mfma_f32_32x32x16_bf16 v[64:79], v[188:191], v[220:223], v[64:79]
	v_mfma_f32_32x32x16_bf16 v[48:63], v[188:191], v[224:227], v[48:63]
	v_mfma_f32_32x32x16_bf16 v[32:47], v[188:191], v[242:245], v[32:47]
	v_mfma_f32_32x32x16_bf16 v[16:31], v[188:191], v[246:249], v[16:31]
	s_mov_b32 s100, 0
	s_nop 15

.LBB0_571:
	s_or_b64 exec, exec, s[8:9]
	v_mov_b32_e32 v0, v1
	s_waitcnt vmcnt(0) lgkmcnt(0)
	s_barrier
	s_lshl_b32 s8, s43, 8
	v_mbcnt_lo_u32_b32 v0, -1, v0
	v_mbcnt_hi_u32_b32 v0, -1, v0
	v_add_u32_e32 v98, s54, v0
	v_mov_b64_e32 v[2:3], s[70:71]
	v_readfirstlane_b32 s9, v98
	s_ashr_i32 s0, s9, 6
	s_lshl_b32 s6, s0, 5
	v_and_b32_e32 v238, 31, v98
	s_add_i32 s20, s6, s8
	v_or_b32_e32 v34, s20, v238
	v_bfe_u32 v237, v98, 5, 1
	v_mad_i64_i32 v[2:3], s[10:11], v34, s46, v[2:3]
	s_lshl_b32 s86, s45, 1
	v_lshl_add_u64 v[2:3], v[2:3], 0, s[86:87]
	v_lshlrev_b32_e32 v0, 4, v237
	v_lshl_add_u64 v[2:3], v[2:3], 0, v[0:1]
	global_load_dwordx4 v[38:41], v[2:3], off
	global_load_dwordx4 v[46:49], v[2:3], off offset:32
	global_load_dwordx4 v[54:57], v[2:3], off offset:64
	global_load_dwordx4 v[62:65], v[2:3], off offset:96
	global_load_dwordx4 v[30:33], v[2:3], off offset:128
	global_load_dwordx4 v[26:29], v[2:3], off offset:160
	global_load_dwordx4 v[22:25], v[2:3], off offset:192
	global_load_dwordx4 v[18:21], v[2:3], off offset:224
	global_load_dwordx4 v[14:17], v[2:3], off offset:256
	global_load_dwordx4 v[6:9], v[2:3], off offset:288
	global_load_dwordx4 v[10:13], v[2:3], off offset:320
	s_nop 0
	global_load_dwordx4 v[2:5], v[2:3], off offset:352
	v_ashrrev_i32_e32 v35, 31, v34
	v_lshl_add_u64 v[34:35], v[34:35], 2, s[68:69]
	global_load_dword v239, v[34:35], off
	s_lshl_b32 s7, s0, 2
	v_bfe_u32 v102, v98, 3, 1
	v_mov_b64_e32 v[100:101], s[66:67]
	s_lshl_b32 s0, s0, 10
	s_add_i32 s0, s0, 0
	s_mov_b32 m0, s0
	s_waitcnt vmcnt(12)
	v_lshlrev_b32_e32 v118, 16, v38
	v_and_b32_e32 v119, 0xffff0000, v38
	v_lshlrev_b32_e32 v120, 16, v39
	v_and_b32_e32 v121, 0xffff0000, v39
	v_pk_mul_f32 v[34:35], v[118:119], v[118:119]
	v_pk_mul_f32 v[36:37], v[120:121], v[120:121]
	v_lshlrev_b32_e32 v122, 16, v40
	v_and_b32_e32 v123, 0xffff0000, v40
	v_pk_mul_f32 v[38:39], v[122:123], v[122:123]
	v_lshlrev_b32_e32 v124, 16, v41
	v_and_b32_e32 v125, 0xffff0000, v41
	v_add_f32_e32 v36, v36, v37
	v_add_f32_e32 v34, v34, v35
	v_pk_mul_f32 v[40:41], v[124:125], v[124:125]
	s_waitcnt vmcnt(11)
	v_lshlrev_b32_e32 v114, 16, v46
	v_and_b32_e32 v115, 0xffff0000, v46
	v_add_f32_e32 v34, v34, v36
	v_add_f32_e32 v35, v38, v39
	v_pk_mul_f32 v[42:43], v[114:115], v[114:115]
	v_lshlrev_b32_e32 v116, 16, v47
	v_and_b32_e32 v117, 0xffff0000, v47
	v_add_f32_e32 v0, v40, v41
	v_add_f32_e32 v34, v35, v34
	v_pk_mul_f32 v[44:45], v[116:117], v[116:117]
	v_lshlrev_b32_e32 v126, 16, v48
	v_and_b32_e32 v127, 0xffff0000, v48
	v_add_f32_e32 v0, v0, v34
	v_add_f32_e32 v34, v42, v43
	v_pk_mul_f32 v[46:47], v[126:127], v[126:127]
	v_lshlrev_b32_e32 v128, 16, v49
	v_and_b32_e32 v129, 0xffff0000, v49
	v_add_f32_e32 v0, v34, v0
	v_add_f32_e32 v34, v44, v45
	v_pk_mul_f32 v[48:49], v[128:129], v[128:129]
	s_waitcnt vmcnt(10)
	v_lshlrev_b32_e32 v130, 16, v54
	v_and_b32_e32 v131, 0xffff0000, v54
	v_add_f32_e32 v0, v34, v0
	v_add_f32_e32 v34, v46, v47
	v_pk_mul_f32 v[50:51], v[130:131], v[130:131]
	v_lshlrev_b32_e32 v132, 16, v55
	v_and_b32_e32 v133, 0xffff0000, v55
	v_add_f32_e32 v0, v34, v0
	v_add_f32_e32 v34, v48, v49
	v_pk_mul_f32 v[52:53], v[132:133], v[132:133]
	v_lshlrev_b32_e32 v134, 16, v56
	v_and_b32_e32 v135, 0xffff0000, v56
	v_add_f32_e32 v0, v34, v0
	v_add_f32_e32 v34, v50, v51
	v_pk_mul_f32 v[54:55], v[134:135], v[134:135]
	v_lshlrev_b32_e32 v136, 16, v57
	v_and_b32_e32 v137, 0xffff0000, v57
	v_add_f32_e32 v0, v34, v0
	v_add_f32_e32 v34, v52, v53
	v_pk_mul_f32 v[56:57], v[136:137], v[136:137]
	s_waitcnt vmcnt(9)
	v_lshlrev_b32_e32 v138, 16, v62
	v_and_b32_e32 v139, 0xffff0000, v62
	v_add_f32_e32 v0, v34, v0
	v_add_f32_e32 v34, v54, v55
	v_pk_mul_f32 v[58:59], v[138:139], v[138:139]
	v_lshlrev_b32_e32 v140, 16, v63
	v_and_b32_e32 v141, 0xffff0000, v63
	v_add_f32_e32 v0, v34, v0
	v_add_f32_e32 v34, v56, v57
	v_pk_mul_f32 v[60:61], v[140:141], v[140:141]
	v_lshlrev_b32_e32 v142, 16, v64
	v_and_b32_e32 v143, 0xffff0000, v64
	v_add_f32_e32 v0, v34, v0
	v_add_f32_e32 v34, v58, v59
	v_pk_mul_f32 v[62:63], v[142:143], v[142:143]
	v_lshlrev_b32_e32 v144, 16, v65
	v_and_b32_e32 v145, 0xffff0000, v65
	v_add_f32_e32 v0, v34, v0
	v_add_f32_e32 v34, v60, v61
	v_pk_mul_f32 v[64:65], v[144:145], v[144:145]
	s_waitcnt vmcnt(8)
	v_lshlrev_b32_e32 v146, 16, v30
	v_and_b32_e32 v147, 0xffff0000, v30
	v_add_f32_e32 v0, v34, v0
	v_add_f32_e32 v34, v62, v63
	v_pk_mul_f32 v[66:67], v[146:147], v[146:147]
	v_lshlrev_b32_e32 v148, 16, v31
	v_and_b32_e32 v149, 0xffff0000, v31
	v_add_f32_e32 v0, v34, v0
	v_add_f32_e32 v34, v64, v65
	v_pk_mul_f32 v[30:31], v[148:149], v[148:149]
	v_lshlrev_b32_e32 v150, 16, v32
	v_and_b32_e32 v151, 0xffff0000, v32
	v_add_f32_e32 v0, v34, v0
	v_add_f32_e32 v34, v66, v67
	v_pk_mul_f32 v[68:69], v[150:151], v[150:151]
	v_lshlrev_b32_e32 v152, 16, v33
	v_and_b32_e32 v153, 0xffff0000, v33
	v_add_f32_e32 v0, v34, v0
	v_add_f32_e32 v30, v30, v31
	v_pk_mul_f32 v[32:33], v[152:153], v[152:153]
	s_waitcnt vmcnt(7)
	v_lshlrev_b32_e32 v154, 16, v26
	v_and_b32_e32 v155, 0xffff0000, v26
	v_add_f32_e32 v0, v30, v0
	v_add_f32_e32 v30, v68, v69
	v_pk_mul_f32 v[70:71], v[154:155], v[154:155]
	v_lshlrev_b32_e32 v160, 16, v27
	v_and_b32_e32 v161, 0xffff0000, v27
	v_add_f32_e32 v0, v30, v0
	v_add_f32_e32 v30, v32, v33
	v_pk_mul_f32 v[26:27], v[160:161], v[160:161]
	v_lshlrev_b32_e32 v158, 16, v28
	v_and_b32_e32 v159, 0xffff0000, v28
	v_add_f32_e32 v0, v30, v0
	v_add_f32_e32 v30, v70, v71
	v_pk_mul_f32 v[72:73], v[158:159], v[158:159]
	v_lshlrev_b32_e32 v156, 16, v29
	v_and_b32_e32 v157, 0xffff0000, v29
	v_add_f32_e32 v0, v30, v0
	v_add_f32_e32 v26, v26, v27
	v_pk_mul_f32 v[28:29], v[156:157], v[156:157]
	s_waitcnt vmcnt(6)
	v_lshlrev_b32_e32 v162, 16, v22
	v_and_b32_e32 v163, 0xffff0000, v22
	v_add_f32_e32 v0, v26, v0
	v_add_f32_e32 v26, v72, v73
	v_pk_mul_f32 v[74:75], v[162:163], v[162:163]
	v_lshlrev_b32_e32 v166, 16, v23
	v_and_b32_e32 v167, 0xffff0000, v23
	v_add_f32_e32 v0, v26, v0
	v_add_f32_e32 v26, v28, v29
	v_pk_mul_f32 v[22:23], v[166:167], v[166:167]
	v_lshlrev_b32_e32 v164, 16, v24
	v_and_b32_e32 v165, 0xffff0000, v24
	v_add_f32_e32 v0, v26, v0
	v_add_f32_e32 v26, v74, v75
	v_pk_mul_f32 v[76:77], v[164:165], v[164:165]
	v_lshlrev_b32_e32 v168, 16, v25
	v_and_b32_e32 v169, 0xffff0000, v25
	v_add_f32_e32 v0, v26, v0
	v_add_f32_e32 v22, v22, v23
	v_pk_mul_f32 v[24:25], v[168:169], v[168:169]
	s_waitcnt vmcnt(5)
	v_lshlrev_b32_e32 v170, 16, v18
	v_and_b32_e32 v171, 0xffff0000, v18
	v_add_f32_e32 v0, v22, v0
	v_add_f32_e32 v22, v76, v77
	v_pk_mul_f32 v[78:79], v[170:171], v[170:171]
	v_lshlrev_b32_e32 v172, 16, v19
	v_and_b32_e32 v173, 0xffff0000, v19
	v_add_f32_e32 v0, v22, v0
	v_add_f32_e32 v22, v24, v25
	v_pk_mul_f32 v[18:19], v[172:173], v[172:173]
	v_lshlrev_b32_e32 v182, 16, v20
	v_and_b32_e32 v183, 0xffff0000, v20
	v_add_f32_e32 v0, v22, v0
	v_add_f32_e32 v22, v78, v79
	v_pk_mul_f32 v[80:81], v[182:183], v[182:183]
	v_lshlrev_b32_e32 v184, 16, v21
	v_and_b32_e32 v185, 0xffff0000, v21
	v_add_f32_e32 v0, v22, v0
	v_add_f32_e32 v18, v18, v19
	v_pk_mul_f32 v[20:21], v[184:185], v[184:185]
	s_waitcnt vmcnt(4)
	v_lshlrev_b32_e32 v188, 16, v14
	v_and_b32_e32 v189, 0xffff0000, v14
	v_add_f32_e32 v0, v18, v0
	v_add_f32_e32 v18, v80, v81
	v_pk_mul_f32 v[82:83], v[188:189], v[188:189]
	v_lshlrev_b32_e32 v186, 16, v15
	v_and_b32_e32 v187, 0xffff0000, v15
	v_add_f32_e32 v0, v18, v0
	v_add_f32_e32 v18, v20, v21
	v_pk_mul_f32 v[14:15], v[186:187], v[186:187]
	v_lshlrev_b32_e32 v196, 16, v16
	v_and_b32_e32 v197, 0xffff0000, v16
	v_add_f32_e32 v0, v18, v0
	v_add_f32_e32 v18, v82, v83
	v_pk_mul_f32 v[84:85], v[196:197], v[196:197]
	v_lshlrev_b32_e32 v194, 16, v17
	v_and_b32_e32 v195, 0xffff0000, v17
	v_add_f32_e32 v0, v18, v0
	v_add_f32_e32 v14, v14, v15
	v_pk_mul_f32 v[16:17], v[194:195], v[194:195]
	s_waitcnt vmcnt(3)
	v_lshlrev_b32_e32 v202, 16, v6
	v_and_b32_e32 v203, 0xffff0000, v6
	v_add_f32_e32 v0, v14, v0
	v_add_f32_e32 v14, v84, v85
	s_waitcnt vmcnt(2)
	v_and_b32_e32 v193, 0xffff0000, v11
	v_pk_mul_f32 v[86:87], v[202:203], v[202:203]
	v_lshlrev_b32_e32 v206, 16, v7
	v_and_b32_e32 v207, 0xffff0000, v7
	v_and_b32_e32 v201, 0xffff0000, v9
	v_add_f32_e32 v0, v14, v0
	v_add_f32_e32 v14, v16, v17
	v_lshlrev_b32_e32 v192, 16, v10
	v_and_b32_e32 v215, 0xffff0000, v10
	v_mov_b32_e32 v214, v193
	v_pk_mul_f32 v[6:7], v[206:207], v[206:207]
	v_lshlrev_b32_e32 v212, 16, v8
	v_and_b32_e32 v223, 0xffff0000, v8
	v_mov_b32_e32 v222, v201
	v_add_f32_e32 v0, v14, v0
	v_add_f32_e32 v14, v86, v87
	v_lshlrev_b32_e32 v190, 16, v11
	v_mov_b32_e32 v191, v192
	v_pk_mul_f32 v[10:11], v[214:215], v[214:215]
	v_lshlrev_b32_e32 v220, 16, v9
	v_mov_b32_e32 v221, v212
	v_pk_mul_f32 v[8:9], v[222:223], v[222:223]
	v_add_f32_e32 v0, v14, v0
	v_add_f32_e32 v6, v6, v7
	v_pk_fma_f32 v[10:11], v[190:191], v[190:191], v[10:11]
	v_and_b32_e32 v191, 0xffff0000, v13
	v_pk_fma_f32 v[8:9], v[220:221], v[220:221], v[8:9]
	v_add_f32_e32 v0, v6, v0
	v_lshlrev_b32_e32 v200, 16, v12
	v_and_b32_e32 v217, 0xffff0000, v12
	v_mov_b32_e32 v216, v191
	v_add_f32_e32 v0, v9, v0
	v_lshlrev_b32_e32 v198, 16, v13
	v_mov_b32_e32 v199, v200
	v_pk_mul_f32 v[12:13], v[216:217], v[216:217]
	v_add_f32_e32 v0, v8, v0
	v_pk_fma_f32 v[12:13], v[198:199], v[198:199], v[12:13]
	s_waitcnt vmcnt(1)
	v_and_b32_e32 v199, 0xffff0000, v3
	v_add_f32_e32 v0, v11, v0
	v_lshlrev_b32_e32 v204, 16, v2
	v_and_b32_e32 v219, 0xffff0000, v2
	v_mov_b32_e32 v218, v199
	v_add_f32_e32 v0, v10, v0
	v_lshlrev_b32_e32 v208, 16, v3
	v_mov_b32_e32 v209, v204
	v_pk_mul_f32 v[2:3], v[218:219], v[218:219]
	v_and_b32_e32 v205, 0xffff0000, v5
	v_add_f32_e32 v0, v13, v0
	v_pk_fma_f32 v[2:3], v[208:209], v[208:209], v[2:3]
	v_lshlrev_b32_e32 v210, 16, v4
	v_and_b32_e32 v225, 0xffff0000, v4
	v_mov_b32_e32 v224, v205
	v_add_f32_e32 v0, v12, v0
	v_lshlrev_b32_e32 v226, 16, v5
	v_mov_b32_e32 v227, v210
	v_pk_mul_f32 v[4:5], v[224:225], v[224:225]
	v_add_f32_e32 v0, v3, v0
	v_pk_fma_f32 v[4:5], v[226:227], v[226:227], v[4:5]
	v_add_f32_e32 v0, v2, v0
	v_add_f32_e32 v0, v5, v0
	v_add_f32_e32 v209, v4, v0
	v_and_b32_e32 v0, 32, v98
	global_load_dwordx4 v[2:5], v0, s[24:25] offset:16
	global_load_dwordx4 v[14:17], v0, s[24:25]
	global_load_dwordx4 v[18:21], v0, s[24:25] offset:80
	global_load_dwordx4 v[22:25], v0, s[24:25] offset:64
	global_load_dwordx4 v[26:29], v0, s[24:25] offset:144
	global_load_dwordx4 v[30:33], v0, s[24:25] offset:128
	global_load_dwordx4 v[34:37], v0, s[24:25] offset:208
	global_load_dwordx4 v[38:41], v0, s[24:25] offset:192
	global_load_dwordx4 v[42:45], v0, s[24:25] offset:272
	global_load_dwordx4 v[46:49], v0, s[24:25] offset:256
	global_load_dwordx4 v[50:53], v0, s[24:25] offset:336
	global_load_dwordx4 v[54:57], v0, s[24:25] offset:320
	global_load_dwordx4 v[58:61], v0, s[24:25] offset:400
	global_load_dwordx4 v[62:65], v0, s[24:25] offset:384
	global_load_dwordx4 v[66:69], v0, s[24:25] offset:464
	global_load_dwordx4 v[70:73], v0, s[24:25] offset:448
	global_load_dwordx4 v[78:81], v0, s[24:25] offset:528
	global_load_dwordx4 v[86:89], v0, s[24:25] offset:512
	global_load_dwordx4 v[74:77], v0, s[24:25] offset:656
	global_load_dwordx4 v[82:85], v0, s[24:25] offset:640
	global_load_dwordx4 v[10:13], v0, s[24:25] offset:592
	global_load_dwordx4 v[90:93], v0, s[24:25] offset:576
	global_load_dwordx4 v[6:9], v0, s[24:25] offset:720
	global_load_dwordx4 v[94:97], v0, s[24:25] offset:704
	v_bfe_u32 v0, v98, 4, 2
	v_or_b32_e32 v99, s7, v0
	v_lshlrev_b32_e32 v99, 1, v99
	v_bitop3_b32 v0, s7, v98, v0 bitop3:0x36
	v_or_b32_e32 v103, v99, v102
	v_mad_i64_i32 v[100:101], s[10:11], v103, s46, v[100:101]
	v_lshlrev_b32_e32 v0, 4, v0
	v_lshl_add_u64 v[100:101], v[100:101], 0, s[86:87]
	v_and_b32_e32 v0, 0x70, v0
	v_add_u32_e32 v99, s44, v99
	v_lshl_add_u64 v[174:175], v[100:101], 0, v[0:1]
	v_or_b32_e32 v100, v99, v102
	v_ashrrev_i32_e32 v101, 31, v100
	v_lshlrev_b64 v[100:101], 15, v[100:101]
	global_load_lds_dwordx4 v[174:175], off
	v_lshl_add_u64 v[102:103], v[174:175], 0, s[94:95]
	s_add_i32 m0, s0, 0x2000
	v_lshl_add_u64 v[100:101], s[12:13], 0, v[100:101]
	global_load_lds_dwordx4 v[102:103], off
	v_lshl_add_u64 v[102:103], v[174:175], 0, s[96:97]
	s_add_i32 m0, s0, 0x4000
	v_lshl_add_u64 v[180:181], v[100:101], 0, v[0:1]
	global_load_lds_dwordx4 v[102:103], off
	s_add_i32 m0, s0, 0x6000
	v_lshl_add_u64 v[100:101], v[180:181], 0, s[92:93]
	global_load_lds_dwordx4 v[180:181], off
	s_add_i32 m0, s0, 0x8000
	s_mov_b64 s[10:11], 0x30000
	global_load_lds_dwordx4 v[100:101], off
	v_lshl_add_u64 v[100:101], v[174:175], 0, s[10:11]
	s_add_i32 m0, s0, 0xa000
	s_mov_b64 s[10:11], 0x30080
	global_load_lds_dwordx4 v[100:101], off
	v_lshl_add_u64 v[100:101], v[174:175], 0, s[10:11]
	s_add_i32 m0, s0, 0xc000
	s_mov_b64 s[10:11], 0x30100
	global_load_lds_dwordx4 v[100:101], off
	v_lshl_add_u64 v[100:101], v[174:175], 0, s[10:11]
	s_add_i32 m0, s0, 0xe000
	s_mov_b64 s[10:11], 0x200080
	global_load_lds_dwordx4 v[100:101], off
	s_add_i32 m0, s0, 0x10000
	v_lshl_add_u64 v[100:101], v[180:181], 0, s[94:95]
	global_load_lds_dwordx4 v[100:101], off
	v_lshl_add_u64 v[100:101], v[180:181], 0, s[10:11]
	s_add_i32 m0, s0, 0x12000
	ds_bpermute_b32 v211, v231, v209
	global_load_lds_dwordx4 v[100:101], off
	s_waitcnt vmcnt(5)
	s_barrier
	s_cmp_lt_i32 s43, 0
	s_cbranch_scc1 .LBB0_582
	v_lshlrev_b32_e32 v0, 3, v237
	v_lshlrev_b32_e32 v0, 2, v0
	v_and_b32_e32 v222, 63, v98
	global_load_dwordx4 v[98:101], v0, s[26:27] offset:192
	global_load_dwordx4 v[102:105], v0, s[26:27] offset:176
	global_load_dwordx4 v[106:109], v0, s[26:27] offset:240
	global_load_dwordx4 v[110:113], v0, s[26:27] offset:256
	s_waitcnt lgkmcnt(0)
	v_add_f32_e32 v0, v209, v211
	v_fmamk_f32 v0, v0, 0x3baaaaab, v232
	v_cmp_gt_f32_e32 vcc, s5, v0
	v_mul_f32_e32 v176, 0x4b800000, v0
	v_mov_b32_e32 v213, v223
	v_cndmask_b32_e32 v0, v0, v176, vcc
	v_rsq_f32_e32 v0, v0
	s_waitcnt vmcnt(0)
	v_cvt_f32_i32_e32 v223, v239
	v_mov_b32_e32 v221, v201
	v_mov_b32_e32 v227, v205
	v_mul_f32_e32 v176, 0x45800000, v0
	v_cndmask_b32_e32 v0, v0, v176, vcc
	v_mul_f32_e32 v0, 0x3dd53b94, v0
	v_mov_b32_e32 v205, v219
	v_mov_b32_e32 v201, v217
	v_pk_mul_f32 v[216:217], v[0:1], v[220:221] op_sel_hi:[0,1]
	v_mov_b32_e32 v211, v225
	v_mov_b32_e32 v209, v199
	v_mov_b32_e32 v199, v191
	v_mov_b32_e32 v191, v193
	v_mov_b32_e32 v193, v215
	v_pk_mul_f32 v[214:215], v[0:1], v[226:227] op_sel_hi:[0,1]
	s_lshl_b32 s21, s43, 2
	s_ashr_i32 s9, s9, 7
	s_mov_b32 s7, 2
	s_add_i32 s9, s9, s21
	s_add_i32 s21, s21, 4
	s_mov_b32 s28, 0
	s_movk_i32 s86, 0x80
	s_mov_b32 s33, 0
	v_mul_f32_e32 v99, v99, v223
	v_mul_f32_e32 v98, v98, v223
	v_mul_f32_e32 v109, v109, v223
	v_mul_f32_e32 v113, v113, v223
	v_cvt_f64_f32_e32 v[176:177], v113
	v_mul_f64 v[178:179], v[176:177], s[84:85]
	v_rndne_f64_e32 v[178:179], v[178:179]
	v_fma_f64 v[176:177], v[176:177], s[84:85], -v[178:179]
	v_cvt_f32_f64_e32 v113, v[176:177]
	v_mul_f32_e32 v112, v112, v223
	v_cos_f32_e32 v219, v113
	v_sin_f32_e32 v221, v113
	v_cvt_f64_f32_e32 v[112:113], v112
	v_mul_f64 v[176:177], v[112:113], s[84:85]
	v_rndne_f64_e32 v[176:177], v[176:177]
	v_fma_f64 v[112:113], v[112:113], s[84:85], -v[176:177]
	v_cvt_f32_f64_e32 v112, v[112:113]
	v_mul_f32_e32 v111, v111, v223
	v_sin_f32_e32 v220, v112
	v_cos_f32_e32 v218, v112
	v_cvt_f64_f32_e32 v[112:113], v111
	v_mul_f64 v[176:177], v[112:113], s[84:85]
	v_rndne_f64_e32 v[176:177], v[176:177]
	v_mul_f32_e32 v110, v110, v223
	v_fma_f64 v[112:113], v[112:113], s[84:85], -v[176:177]
	v_pk_mul_f32 v[178:179], v[0:1], v[210:211] op_sel_hi:[0,1]
	v_cvt_f64_f32_e32 v[210:211], v110
	v_cvt_f32_f64_e32 v176, v[112:113]
	v_pk_mul_f32 v[112:113], v[0:1], v[212:213] op_sel_hi:[0,1]
	v_mul_f64 v[212:213], v[210:211], s[84:85]
	v_rndne_f64_e32 v[212:213], v[212:213]
	v_fma_f64 v[210:211], v[210:211], s[84:85], -v[212:213]
	v_sin_f32_e32 v111, v176
	v_cos_f32_e32 v177, v176
	v_cvt_f32_f64_e32 v176, v[210:211]
	v_sin_f32_e32 v110, v176
	v_cos_f32_e32 v176, v176
	v_pk_mul_f32 v[6:7], v[6:7], v[178:179]
	v_pk_mul_f32 v[112:113], v[10:11], v[112:113]
	v_mul_f32_e32 v108, v108, v223
	v_pk_mul_f32 v[10:11], v[176:177], v[6:7]
	v_pk_mul_f32 v[6:7], v[110:111], v[6:7]
	v_pk_fma_f32 v[10:11], v[110:111], v[112:113], v[10:11]
	v_cvt_f64_f32_e32 v[110:111], v109
	v_pk_fma_f32 v[6:7], v[176:177], v[112:113], v[6:7] neg_lo:[0,0,1] neg_hi:[0,0,1]
	v_mul_f64 v[112:113], v[110:111], s[84:85]
	v_rndne_f64_e32 v[112:113], v[112:113]
	v_cvt_f64_f32_e32 v[178:179], v108
	v_fma_f64 v[110:111], v[110:111], s[84:85], -v[112:113]
	v_pk_mul_f32 v[112:113], v[0:1], v[206:207] op_sel_hi:[0,1]
	v_mul_f64 v[206:207], v[178:179], s[84:85]
	v_rndne_f64_e32 v[206:207], v[206:207]
	v_cvt_f32_f64_e32 v110, v[110:111]
	v_fma_f64 v[178:179], v[178:179], s[84:85], -v[206:207]
	v_sin_f32_e32 v109, v110
	v_cos_f32_e32 v111, v110
	v_cvt_f32_f64_e32 v110, v[178:179]
	v_sin_f32_e32 v108, v110
	v_cos_f32_e32 v110, v110
	v_pk_mul_f32 v[176:177], v[0:1], v[208:209] op_sel_hi:[0,1]
	v_pk_mul_f32 v[96:97], v[96:97], v[176:177]
	v_pk_mul_f32 v[92:93], v[92:93], v[112:113]
	v_pk_mul_f32 v[112:113], v[110:111], v[96:97]
	v_pk_mul_f32 v[96:97], v[108:109], v[96:97]
	v_pk_fma_f32 v[208:209], v[108:109], v[92:93], v[112:113]
	v_pk_fma_f32 v[206:207], v[110:111], v[92:93], v[96:97] neg_lo:[0,0,1] neg_hi:[0,0,1]
	v_mul_f32_e32 v92, v107, v223
	v_cvt_f64_f32_e32 v[92:93], v92
	v_mul_f64 v[96:97], v[92:93], s[84:85]
	v_rndne_f64_e32 v[96:97], v[96:97]
	v_fma_f64 v[92:93], v[92:93], s[84:85], -v[96:97]
	v_cvt_f32_f64_e32 v92, v[92:93]
	v_sin_f32_e32 v93, v92
	v_cos_f32_e32 v107, v92
	v_mul_f32_e32 v92, v106, v223
	v_cvt_f64_f32_e32 v[110:111], v92
	v_mul_f64 v[112:113], v[110:111], s[84:85]
	v_rndne_f64_e32 v[112:113], v[112:113]
	v_fma_f64 v[110:111], v[110:111], s[84:85], -v[112:113]
	v_cvt_f32_f64_e32 v106, v[110:111]
	v_sin_f32_e32 v92, v106
	v_cos_f32_e32 v106, v106
	v_pk_mul_f32 v[108:109], v[0:1], v[204:205] op_sel_hi:[0,1]
	v_pk_mul_f32 v[96:97], v[0:1], v[202:203] op_sel_hi:[0,1]
	v_pk_mul_f32 v[94:95], v[94:95], v[108:109]
	v_pk_mul_f32 v[90:91], v[90:91], v[96:97]
	v_pk_mul_f32 v[96:97], v[106:107], v[94:95]
	v_cvt_f64_f32_e32 v[178:179], v99
	v_pk_fma_f32 v[204:205], v[92:93], v[90:91], v[96:97]
	v_pk_mul_f32 v[92:93], v[92:93], v[94:95]
	v_mul_f32_e32 v100, v100, v223
	v_pk_fma_f32 v[202:203], v[106:107], v[90:91], v[92:93] neg_lo:[0,0,1] neg_hi:[0,0,1]
	v_mul_f32_e32 v90, v102, v223
	v_cvt_f64_f32_e32 v[90:91], v90
	v_mul_f64 v[92:93], v[90:91], s[84:85]
	v_rndne_f64_e32 v[92:93], v[92:93]
	v_fma_f64 v[90:91], v[90:91], s[84:85], -v[92:93]
	v_cvt_f32_f64_e32 v91, v[90:91]
	v_sin_f32_e32 v90, v91
	v_cos_f32_e32 v94, v91
	v_mul_f32_e32 v91, v103, v223
	v_cvt_f64_f32_e32 v[102:103], v91
	v_mul_f64 v[106:107], v[102:103], s[84:85]
	v_rndne_f64_e32 v[106:107], v[106:107]
	v_fma_f64 v[102:103], v[102:103], s[84:85], -v[106:107]
	v_cvt_f32_f64_e32 v95, v[102:103]
	v_mul_f32_e32 v102, v104, v223
	v_cvt_f64_f32_e32 v[102:103], v102
	v_mul_f64 v[106:107], v[102:103], s[84:85]
	v_rndne_f64_e32 v[106:107], v[106:107]
	v_fma_f64 v[102:103], v[102:103], s[84:85], -v[106:107]
	v_cvt_f32_f64_e32 v103, v[102:103]
	v_sin_f32_e32 v102, v103
	v_cos_f32_e32 v104, v103
	v_mul_f32_e32 v103, v105, v223
	v_cvt_f64_f32_e32 v[110:111], v103
	v_mul_f64 v[112:113], v[110:111], s[84:85]
	v_rndne_f64_e32 v[112:113], v[112:113]
	v_fma_f64 v[110:111], v[110:111], s[84:85], -v[112:113]
	v_pk_mul_f32 v[106:107], v[0:1], v[186:187] op_sel_hi:[0,1]
	v_cvt_f32_f64_e32 v105, v[110:111]
	v_cvt_f64_f32_e32 v[110:111], v98
	v_mul_f64 v[186:187], v[178:179], s[84:85]
	v_mul_f64 v[112:113], v[110:111], s[84:85]
	v_rndne_f64_e32 v[186:187], v[186:187]
	v_sin_f32_e32 v91, v95
	v_cos_f32_e32 v95, v95
	v_rndne_f64_e32 v[112:113], v[112:113]
	v_fma_f64 v[178:179], v[178:179], s[84:85], -v[186:187]
	v_mul_f32_e32 v101, v101, v223
	v_pk_mul_f32 v[108:109], v[0:1], v[190:191] op_sel_hi:[0,1]
	v_fma_f64 v[110:111], v[110:111], s[84:85], -v[112:113]
	v_cvt_f32_f64_e32 v113, v[178:179]
	v_cvt_f64_f32_e32 v[178:179], v100
	v_cvt_f64_f32_e32 v[190:191], v101
	v_pk_mul_f32 v[92:93], v[0:1], v[188:189] op_sel_hi:[0,1]
	v_pk_mul_f32 v[96:97], v[0:1], v[192:193] op_sel_hi:[0,1]
	v_sin_f32_e32 v103, v105
	v_cos_f32_e32 v105, v105
	v_mul_f64 v[186:187], v[178:179], s[84:85]
	v_mul_f64 v[192:193], v[190:191], s[84:85]
	v_cvt_f32_f64_e32 v112, v[110:111]
	v_rndne_f64_e32 v[186:187], v[186:187]
	v_rndne_f64_e32 v[192:193], v[192:193]
	v_pk_mul_f32 v[86:87], v[86:87], v[92:93]
	v_pk_mul_f32 v[92:93], v[82:83], v[96:97]
	v_sin_f32_e32 v98, v112
	v_cos_f32_e32 v112, v112
	v_sin_f32_e32 v99, v113
	v_cos_f32_e32 v113, v113
	v_fma_f64 v[178:179], v[178:179], s[84:85], -v[186:187]
	v_fma_f64 v[190:191], v[190:191], s[84:85], -v[192:193]
	v_pk_mul_f32 v[82:83], v[94:95], v[92:93]
	v_cvt_f32_f64_e32 v186, v[178:179]
	v_cvt_f32_f64_e32 v187, v[190:191]
	v_pk_fma_f32 v[82:83], v[90:91], v[86:87], v[82:83]
	v_pk_mul_f32 v[90:91], v[90:91], v[92:93]
	v_pk_mul_f32 v[84:85], v[84:85], v[108:109]
	v_pk_mul_f32 v[176:177], v[0:1], v[200:201] op_sel_hi:[0,1]
	v_sin_f32_e32 v100, v186
	v_cos_f32_e32 v186, v186
	v_sin_f32_e32 v101, v187
	v_cos_f32_e32 v187, v187
	v_pk_fma_f32 v[86:87], v[94:95], v[86:87], v[90:91] neg_lo:[0,0,1] neg_hi:[0,0,1]
	v_pk_mul_f32 v[88:89], v[88:89], v[106:107]
	v_pk_mul_f32 v[90:91], v[104:105], v[84:85]
	v_pk_mul_f32 v[84:85], v[102:103], v[84:85]
	v_pk_mul_f32 v[110:111], v[0:1], v[196:197] op_sel_hi:[0,1]
	v_pk_fma_f32 v[84:85], v[104:105], v[88:89], v[84:85] neg_lo:[0,0,1] neg_hi:[0,0,1]
	v_pk_mul_f32 v[74:75], v[74:75], v[176:177]
	v_pk_mul_f32 v[188:189], v[0:1], v[198:199] op_sel_hi:[0,1]
	v_cvt_pk_bf16_f32 v86, v86, v87
	v_cvt_pk_bf16_f32 v87, v84, v85
	v_pk_mul_f32 v[78:79], v[78:79], v[110:111]
	v_pk_mul_f32 v[84:85], v[112:113], v[74:75]
	v_pk_mul_f32 v[74:75], v[98:99], v[74:75]
	v_pk_mul_f32 v[178:179], v[0:1], v[194:195] op_sel_hi:[0,1]
	v_pk_fma_f32 v[74:75], v[112:113], v[78:79], v[74:75] neg_lo:[0,0,1] neg_hi:[0,0,1]
	v_pk_mul_f32 v[76:77], v[76:77], v[188:189]
	v_pk_fma_f32 v[90:91], v[102:103], v[88:89], v[90:91]
	v_pk_fma_f32 v[84:85], v[98:99], v[78:79], v[84:85]
	v_cvt_pk_bf16_f32 v88, v74, v75
	v_pk_mul_f32 v[74:75], v[80:81], v[178:179]
	v_pk_mul_f32 v[78:79], v[186:187], v[76:77]
	v_pk_mul_f32 v[76:77], v[100:101], v[76:77]
	v_pk_fma_f32 v[78:79], v[100:101], v[74:75], v[78:79]
	v_pk_fma_f32 v[74:75], v[186:187], v[74:75], v[76:77] neg_lo:[0,0,1] neg_hi:[0,0,1]
	v_cvt_pk_bf16_f32 v82, v82, v83
	v_cvt_pk_bf16_f32 v89, v74, v75
	v_pk_mul_f32 v[74:75], v[0:1], v[170:171] op_sel_hi:[0,1]
	v_pk_mul_f32 v[70:71], v[70:71], v[74:75]
	v_cvt_pk_bf16_f32 v83, v90, v91
	v_cvt_pk_bf16_f32 v90, v70, v71
	v_pk_mul_f32 v[70:71], v[0:1], v[172:173] op_sel_hi:[0,1]
	v_pk_mul_f32 v[70:71], v[72:73], v[70:71]
	v_cvt_pk_bf16_f32 v84, v84, v85
	v_cvt_pk_bf16_f32 v91, v70, v71
	v_pk_mul_f32 v[70:71], v[0:1], v[182:183] op_sel_hi:[0,1]
	v_pk_mul_f32 v[66:67], v[66:67], v[70:71]
	v_cvt_pk_bf16_f32 v85, v78, v79
	v_cvt_pk_bf16_f32 v92, v66, v67
	v_pk_mul_f32 v[66:67], v[0:1], v[184:185] op_sel_hi:[0,1]
	v_pk_mul_f32 v[66:67], v[68:69], v[66:67]
	s_nop 0
	v_cvt_pk_bf16_f32 v93, v66, v67
	v_pk_mul_f32 v[66:67], v[0:1], v[162:163] op_sel_hi:[0,1]
	v_pk_mul_f32 v[62:63], v[62:63], v[66:67]
	s_nop 0
	v_cvt_pk_bf16_f32 v94, v62, v63
	v_pk_mul_f32 v[62:63], v[0:1], v[166:167] op_sel_hi:[0,1]
	v_pk_mul_f32 v[62:63], v[64:65], v[62:63]
	s_nop 0
	v_cvt_pk_bf16_f32 v95, v62, v63
	v_pk_mul_f32 v[62:63], v[0:1], v[164:165] op_sel_hi:[0,1]
	v_pk_mul_f32 v[58:59], v[58:59], v[62:63]
	s_nop 0
	v_cvt_pk_bf16_f32 v96, v58, v59
	v_pk_mul_f32 v[58:59], v[0:1], v[168:169] op_sel_hi:[0,1]
	v_pk_mul_f32 v[58:59], v[60:61], v[58:59]
	s_nop 0
	v_cvt_pk_bf16_f32 v97, v58, v59
	v_pk_mul_f32 v[58:59], v[0:1], v[154:155] op_sel_hi:[0,1]
	v_pk_mul_f32 v[54:55], v[54:55], v[58:59]
	s_nop 0
	v_cvt_pk_bf16_f32 v98, v54, v55
	v_pk_mul_f32 v[54:55], v[0:1], v[160:161] op_sel_hi:[0,1]
	v_pk_mul_f32 v[54:55], v[56:57], v[54:55]
	s_nop 0
	v_cvt_pk_bf16_f32 v99, v54, v55
	v_pk_mul_f32 v[54:55], v[0:1], v[158:159] op_sel_hi:[0,1]
	v_pk_mul_f32 v[50:51], v[50:51], v[54:55]
	s_nop 0
	v_cvt_pk_bf16_f32 v100, v50, v51
	v_pk_mul_f32 v[50:51], v[0:1], v[156:157] op_sel_hi:[0,1]
	v_pk_mul_f32 v[50:51], v[52:53], v[50:51]
	s_nop 0
	v_cvt_pk_bf16_f32 v101, v50, v51
	v_pk_mul_f32 v[50:51], v[0:1], v[146:147] op_sel_hi:[0,1]
	v_pk_mul_f32 v[46:47], v[46:47], v[50:51]
	v_mov_b32_e32 v50, 0
	v_cvt_pk_bf16_f32 v102, v46, v47
	v_pk_mul_f32 v[46:47], v[0:1], v[148:149] op_sel_hi:[0,1]
	v_pk_mul_f32 v[46:47], v[48:49], v[46:47]
	s_nop 0
	v_cvt_pk_bf16_f32 v103, v46, v47
	v_pk_mul_f32 v[46:47], v[0:1], v[150:151] op_sel_hi:[0,1]
	v_pk_mul_f32 v[42:43], v[42:43], v[46:47]
	s_nop 0
	v_cvt_pk_bf16_f32 v104, v42, v43
	v_pk_mul_f32 v[42:43], v[0:1], v[152:153] op_sel_hi:[0,1]
	v_pk_mul_f32 v[42:43], v[44:45], v[42:43]
	s_nop 0
	v_cvt_pk_bf16_f32 v105, v42, v43
	v_pk_mul_f32 v[42:43], v[0:1], v[138:139] op_sel_hi:[0,1]
	v_pk_mul_f32 v[38:39], v[38:39], v[42:43]
	s_nop 0
	v_cvt_pk_bf16_f32 v106, v38, v39
	v_pk_mul_f32 v[38:39], v[0:1], v[140:141] op_sel_hi:[0,1]
	v_pk_mul_f32 v[38:39], v[40:41], v[38:39]
	s_nop 0
	v_cvt_pk_bf16_f32 v107, v38, v39
	v_pk_mul_f32 v[38:39], v[0:1], v[142:143] op_sel_hi:[0,1]
	v_pk_mul_f32 v[34:35], v[34:35], v[38:39]
	s_nop 0
	v_cvt_pk_bf16_f32 v108, v34, v35
	v_pk_mul_f32 v[34:35], v[0:1], v[144:145] op_sel_hi:[0,1]
	v_pk_mul_f32 v[34:35], v[36:37], v[34:35]
	s_nop 0
	v_cvt_pk_bf16_f32 v109, v34, v35
	v_pk_mul_f32 v[34:35], v[0:1], v[130:131] op_sel_hi:[0,1]
	v_pk_mul_f32 v[30:31], v[30:31], v[34:35]
	v_mov_b32_e32 v34, 0
	v_cvt_pk_bf16_f32 v110, v30, v31
	v_pk_mul_f32 v[30:31], v[0:1], v[132:133] op_sel_hi:[0,1]
	v_pk_mul_f32 v[30:31], v[32:33], v[30:31]
	s_nop 0
	v_cvt_pk_bf16_f32 v111, v30, v31
	v_pk_mul_f32 v[30:31], v[0:1], v[134:135] op_sel_hi:[0,1]
	v_pk_mul_f32 v[26:27], v[26:27], v[30:31]
	s_nop 0
	v_cvt_pk_bf16_f32 v112, v26, v27
	v_pk_mul_f32 v[26:27], v[0:1], v[136:137] op_sel_hi:[0,1]
	v_pk_mul_f32 v[26:27], v[28:29], v[26:27]
	s_nop 0
	v_cvt_pk_bf16_f32 v113, v26, v27
	v_pk_mul_f32 v[26:27], v[0:1], v[114:115] op_sel_hi:[0,1]
	v_pk_mul_f32 v[22:23], v[22:23], v[26:27]
	s_nop 0
	v_cvt_pk_bf16_f32 v114, v22, v23
	v_pk_mul_f32 v[22:23], v[0:1], v[116:117] op_sel_hi:[0,1]
	v_pk_mul_f32 v[22:23], v[24:25], v[22:23]
	s_nop 0
	v_cvt_pk_bf16_f32 v115, v22, v23
	v_pk_mul_f32 v[22:23], v[0:1], v[126:127] op_sel_hi:[0,1]
	v_pk_mul_f32 v[18:19], v[18:19], v[22:23]
	v_cvt_pk_bf16_f32 v126, v202, v203
	v_cvt_pk_bf16_f32 v116, v18, v19
	v_pk_mul_f32 v[18:19], v[0:1], v[128:129] op_sel_hi:[0,1]
	v_pk_mul_f32 v[18:19], v[20:21], v[18:19]
	v_cvt_pk_bf16_f32 v128, v6, v7
	v_cvt_pk_bf16_f32 v117, v18, v19
	v_pk_mul_f32 v[18:19], v[0:1], v[118:119] op_sel_hi:[0,1]
	v_pk_mul_f32 v[14:15], v[14:15], v[18:19]
	v_cvt_pk_bf16_f32 v127, v206, v207
	v_cvt_pk_bf16_f32 v118, v14, v15
	v_pk_mul_f32 v[14:15], v[0:1], v[120:121] op_sel_hi:[0,1]
	v_pk_mul_f32 v[14:15], v[16:17], v[14:15]
	v_mov_b32_e32 v18, 0
	v_cvt_pk_bf16_f32 v119, v14, v15
	v_pk_mul_f32 v[14:15], v[0:1], v[122:123] op_sel_hi:[0,1]
	v_pk_mul_f32 v[2:3], v[2:3], v[14:15]
	v_cvt_pk_bf16_f32 v122, v204, v205
	v_cvt_pk_bf16_f32 v120, v2, v3
	v_pk_mul_f32 v[2:3], v[0:1], v[124:125] op_sel_hi:[0,1]
	v_pk_mul_f32 v[2:3], v[4:5], v[2:3]
	v_pk_mul_f32 v[4:5], v[8:9], v[214:215]
	v_cvt_pk_bf16_f32 v121, v2, v3
	v_pk_mul_f32 v[2:3], v[12:13], v[216:217]
	v_pk_mul_f32 v[6:7], v[218:219], v[4:5]
	v_pk_mul_f32 v[4:5], v[220:221], v[4:5]
	v_pk_fma_f32 v[6:7], v[220:221], v[2:3], v[6:7]
	v_pk_fma_f32 v[2:3], v[218:219], v[2:3], v[4:5] neg_lo:[0,0,1] neg_hi:[0,0,1]
	v_mov_b32_e32 v0, 0
	v_cvt_pk_bf16_f32 v123, v208, v209
	v_cvt_pk_bf16_f32 v124, v10, v11
	v_cvt_pk_bf16_f32 v125, v6, v7
	v_cvt_pk_bf16_f32 v129, v2, v3
	v_mov_b32_e32 v2, 0
	v_mov_b32_e32 v3, v0
	v_mov_b32_e32 v4, v0
	v_mov_b32_e32 v5, v0
	v_mov_b32_e32 v6, v0
	v_mov_b32_e32 v7, v0
	v_mov_b32_e32 v8, v0
	v_mov_b32_e32 v9, v0
	v_mov_b32_e32 v10, v0
	v_mov_b32_e32 v11, v0
	v_mov_b32_e32 v12, v0
	v_mov_b32_e32 v13, v0
	v_mov_b32_e32 v14, v0
	v_mov_b32_e32 v15, v0
	v_mov_b32_e32 v16, v0
	v_mov_b32_e32 v17, v0
	v_mov_b32_e32 v19, v0
	v_mov_b32_e32 v20, v0
	v_mov_b32_e32 v21, v0
	v_mov_b32_e32 v22, v0
	v_mov_b32_e32 v23, v0
	v_mov_b32_e32 v24, v0
	v_mov_b32_e32 v25, v0
	v_mov_b32_e32 v26, v0
	v_mov_b32_e32 v27, v0
	v_mov_b32_e32 v28, v0
	v_mov_b32_e32 v29, v0
	v_mov_b32_e32 v30, v0
	v_mov_b32_e32 v31, v0
	v_mov_b32_e32 v32, v0
	v_mov_b32_e32 v33, v0
	v_mov_b32_e32 v35, v0
	v_mov_b32_e32 v36, v0
	v_mov_b32_e32 v37, v0
	v_mov_b32_e32 v38, v0
	v_mov_b32_e32 v39, v0
	v_mov_b32_e32 v40, v0
	v_mov_b32_e32 v41, v0
	v_mov_b32_e32 v42, v0
	v_mov_b32_e32 v43, v0
	v_mov_b32_e32 v44, v0
	v_mov_b32_e32 v45, v0
	v_mov_b32_e32 v46, v0
	v_mov_b32_e32 v47, v0
	v_mov_b32_e32 v48, v0
	v_mov_b32_e32 v49, v0
	v_mov_b32_e32 v51, v0
	v_mov_b32_e32 v52, v0
	v_mov_b32_e32 v53, v0
	v_mov_b32_e32 v54, v0
	v_mov_b32_e32 v55, v0
	v_mov_b32_e32 v56, v0
	v_mov_b32_e32 v57, v0
	v_mov_b32_e32 v58, v0
	v_mov_b32_e32 v59, v0
	v_mov_b32_e32 v60, v0
	v_mov_b32_e32 v61, v0
	v_mov_b32_e32 v62, v0
	v_mov_b32_e32 v63, v0
	v_mov_b32_e32 v64, v0
	v_mov_b32_e32 v65, v0
	v_mov_b32_e32 v208, v222
	v_lshlrev_b32_e32 v211, 3, v208
	v_lshrrev_b32_e32 v209, 1, v208
	v_lshlrev_b32_e32 v210, 7, v208
	v_and_b32_e32 v211, 8, v211
	v_ashrrev_i32_e32 v208, 5, v208
	v_add_u32_e32 v208, v211, v208
	v_and_b32_e32 v210, 0xf00, v210
	v_bitop3_b32 v211, v208, v209, 7 bitop3:0x78
	v_add_u32_e32 v212, 2, v208
	v_add_u32_e32 v213, 4, v208
	v_add_u32_e32 v208, 6, v208
	v_bitop3_b32 v212, v212, v209, 7 bitop3:0x78
	v_bitop3_b32 v213, v213, v209, 7 bitop3:0x78
	v_bitop3_b32 v208, v208, v209, 7 bitop3:0x78
	v_lshl_add_u32 v218, v211, 4, v210
	v_lshl_add_u32 v219, v212, 4, v210
	v_lshl_add_u32 v209, v213, 4, v210
	v_lshl_add_u32 v208, v208, 4, v210
	s_mov_b32 s100, 0
	s_branch .LBB0_574

.LBB0_574:
	s_add_i32 s10, s33, 2
	s_cmp_ge_i32 s10, s21
	s_cselect_b64 s[22:23], -1, 0
	s_mov_b64 s[34:35], -1
	s_cmp_gt_i32 s33, s9
	s_cbranch_scc1 .Lat2_skip
	s_and_b64 vcc, exec, s[22:23]
	s_cbranch_vccnz .Lat2_nodma
	s_setprio 3
	s_mul_i32 s10, s28, 0xa000
	v_add_u32_e32 v198, s10, v218
	v_add_u32_e32 v199, s10, v219
	v_add_u32_e32 v200, s10, v209
	v_add_u32_e32 v201, s10, v208
	ds_read_b128 v[130:133], v198 offset:0
	ds_read_b128 v[134:137], v199 offset:0
	ds_read_b128 v[138:141], v200 offset:0
	ds_read_b128 v[142:145], v201 offset:0
	ds_read_b128 v[146:149], v198 offset:8192
	ds_read_b128 v[150:153], v199 offset:8192
	ds_read_b128 v[154:157], v200 offset:8192
	ds_read_b128 v[158:161], v201 offset:8192
	ds_read_b128 v[162:165], v198 offset:16384
	ds_read_b128 v[166:169], v199 offset:16384
	ds_read_b128 v[170:173], v200 offset:16384
	ds_read_b128 v[176:179], v201 offset:16384
	s_cmp_eq_u32 s100, 0
	s_cbranch_scc1 .Lat2_nopend1
	v_mfma_f32_32x32x16_bf16 v[50:65], v[186:189], v[214:217], v[50:65]
	v_mfma_f32_32x32x16_bf16 v[34:49], v[186:189], v[224:227], v[34:49]
	v_mfma_f32_32x32x16_bf16 v[18:33], v[186:189], v[240:243], v[18:33]
	v_mfma_f32_32x32x16_bf16 v[2:17], v[186:189], v[244:247], v[2:17]
.Lat2_nopend1:
	v_mad_u64_u32 v[204:205], s[10:11], s86, v228, v[174:175]
	s_mul_i32 s10, s7, 0xa000
	s_add_i32 s10, s0, s10
	s_mov_b32 m0, s10
	v_lshl_add_u64 v[206:207], v[204:205], 0, s[94:95]
	global_load_lds_dwordx4 v[204:205], off
	s_add_i32 m0, s10, 0x2000
	v_lshl_add_u64 v[204:205], v[204:205], 0, s[96:97]
	global_load_lds_dwordx4 v[206:207], off
	s_waitcnt lgkmcnt(8)
	v_mfma_f32_32x32x16_bf16 v[66:81], v[130:133], v[118:121], 0
	s_add_i32 m0, s10, 0x4000
	v_mfma_f32_32x32x16_bf16 v[66:81], v[134:137], v[114:117], v[66:81]
	global_load_lds_dwordx4 v[204:205], off
	v_lshl_add_u64 v[204:205], s[86:87], 1, v[180:181]
	s_add_i32 m0, s10, 0x6000
	v_mfma_f32_32x32x16_bf16 v[66:81], v[138:141], v[110:113], v[66:81]
	global_load_lds_dwordx4 v[204:205], off
	v_lshl_add_u64 v[204:205], v[204:205], 0, s[92:93]
	s_add_i32 m0, s10, 0x8000
	v_mfma_f32_32x32x16_bf16 v[66:81], v[142:145], v[106:109], v[66:81]
	global_load_lds_dwordx4 v[204:205], off
	ds_read_b128 v[130:133], v198 offset:4096
	ds_read_b128 v[134:137], v199 offset:4096
	ds_read_b128 v[138:141], v200 offset:4096
	ds_read_b128 v[142:145], v201 offset:4096
	s_waitcnt lgkmcnt(8)
	v_mfma_f32_32x32x16_bf16 v[66:81], v[146:149], v[102:105], v[66:81]
	v_mfma_f32_32x32x16_bf16 v[66:81], v[150:153], v[98:101], v[66:81]
	v_mfma_f32_32x32x16_bf16 v[66:81], v[154:157], v[94:97], v[66:81]
	v_mfma_f32_32x32x16_bf16 v[66:81], v[158:161], v[90:93], v[66:81]
	ds_read_b128 v[146:149], v198 offset:12288
	ds_read_b128 v[150:153], v199 offset:12288
	ds_read_b128 v[154:157], v200 offset:12288
	ds_read_b128 v[158:161], v201 offset:12288
	s_waitcnt lgkmcnt(8)
	v_mfma_f32_32x32x16_bf16 v[66:81], v[162:165], v[86:89], v[66:81]
	v_mfma_f32_32x32x16_bf16 v[66:81], v[166:169], v[126:129], v[66:81]
	v_mfma_f32_32x32x16_bf16 v[66:81], v[170:173], v[82:85], v[66:81]
	v_mfma_f32_32x32x16_bf16 v[66:81], v[176:179], v[122:125], v[66:81]
	s_setprio 2
	ds_read_b128 v[162:165], v198 offset:20480
	ds_read_b128 v[166:169], v199 offset:20480
	ds_read_b128 v[170:173], v200 offset:20480
	ds_read_b128 v[176:179], v201 offset:20480
	s_waitcnt lgkmcnt(8)
	v_mfma_f32_32x32x16_bf16 v[182:197], v[130:133], v[118:121], 0
	v_mfma_f32_32x32x16_bf16 v[182:197], v[134:137], v[114:117], v[182:197]
	v_mfma_f32_32x32x16_bf16 v[182:197], v[138:141], v[110:113], v[182:197]
	v_mfma_f32_32x32x16_bf16 v[182:197], v[142:145], v[106:109], v[182:197]
	ds_read_b128 v[130:133], v198 offset:24576
	ds_read_b128 v[134:137], v198 offset:28672
	ds_read_b128 v[138:141], v198 offset:32768
	ds_read_b128 v[142:145], v198 offset:36864
	s_waitcnt lgkmcnt(8)
	v_mfma_f32_32x32x16_bf16 v[182:197], v[146:149], v[102:105], v[182:197]
	v_med3_f32 v66, v66, s4, v236
	v_exp_f32_e32 v66, v66
	v_med3_f32 v67, v67, s4, v236
	v_exp_f32_e32 v67, v67
	v_mfma_f32_32x32x16_bf16 v[182:197], v[150:153], v[98:101], v[182:197]
	v_med3_f32 v68, v68, s4, v236
	v_exp_f32_e32 v68, v68
	v_med3_f32 v69, v69, s4, v236
	v_exp_f32_e32 v69, v69
	v_mfma_f32_32x32x16_bf16 v[182:197], v[154:157], v[94:97], v[182:197]
	v_med3_f32 v70, v70, s4, v236
	v_exp_f32_e32 v70, v70
	v_med3_f32 v71, v71, s4, v236
	v_exp_f32_e32 v71, v71
	v_mfma_f32_32x32x16_bf16 v[182:197], v[158:161], v[90:93], v[182:197]
	v_med3_f32 v72, v72, s4, v236
	v_exp_f32_e32 v72, v72
	v_med3_f32 v73, v73, s4, v236
	v_exp_f32_e32 v73, v73
	ds_read_b128 v[146:149], v199 offset:24576
	ds_read_b128 v[150:153], v199 offset:28672
	ds_read_b128 v[154:157], v199 offset:32768
	ds_read_b128 v[158:161], v199 offset:36864
	s_waitcnt lgkmcnt(8)
	v_mfma_f32_32x32x16_bf16 v[182:197], v[162:165], v[86:89], v[182:197]
	v_med3_f32 v74, v74, s4, v236
	v_exp_f32_e32 v74, v74
	v_med3_f32 v75, v75, s4, v236
	v_exp_f32_e32 v75, v75
	v_add_f32_e32 v202, v66, v67
	v_add_f32_e32 v202, v202, v68
	v_mfma_f32_32x32x16_bf16 v[182:197], v[166:169], v[126:129], v[182:197]
	v_med3_f32 v76, v76, s4, v236
	v_exp_f32_e32 v76, v76
	v_med3_f32 v77, v77, s4, v236
	v_exp_f32_e32 v77, v77
	v_add_f32_e32 v202, v202, v69
	v_add_f32_e32 v202, v202, v70
	v_mfma_f32_32x32x16_bf16 v[182:197], v[170:173], v[82:85], v[182:197]
	v_med3_f32 v78, v78, s4, v236
	v_exp_f32_e32 v78, v78
	v_med3_f32 v79, v79, s4, v236
	v_exp_f32_e32 v79, v79
	v_add_f32_e32 v202, v202, v71
	v_add_f32_e32 v202, v202, v72
	v_mfma_f32_32x32x16_bf16 v[182:197], v[176:179], v[122:125], v[182:197]
	v_med3_f32 v80, v80, s4, v236
	v_exp_f32_e32 v80, v80
	v_med3_f32 v81, v81, s4, v236
	v_exp_f32_e32 v81, v81
	v_add_f32_e32 v202, v202, v73
	s_setprio 1
	ds_read_b128 v[162:165], v200 offset:24576
	ds_read_b128 v[166:169], v200 offset:28672
	ds_read_b128 v[170:173], v200 offset:32768
	ds_read_b128 v[176:179], v200 offset:36864
	v_cvt_pk_bf16_f32 v66, v66, v67
	v_cvt_pk_bf16_f32 v67, v68, v69
	v_cvt_pk_bf16_f32 v68, v70, v71
	v_cvt_pk_bf16_f32 v69, v72, v73
	v_add_f32_e32 v202, v202, v74
	v_add_f32_e32 v202, v202, v75
	s_waitcnt lgkmcnt(8)
	v_mfma_f32_32x32x16_bf16 v[50:65], v[66:69], v[130:133], v[50:65]
	v_med3_f32 v182, v182, s4, v236
	v_exp_f32_e32 v182, v182
	v_med3_f32 v183, v183, s4, v236
	v_exp_f32_e32 v183, v183
	v_add_f32_e32 v202, v202, v76
	v_add_f32_e32 v202, v202, v77
	v_mfma_f32_32x32x16_bf16 v[34:49], v[66:69], v[134:137], v[34:49]
	v_med3_f32 v184, v184, s4, v236
	v_exp_f32_e32 v184, v184
	v_med3_f32 v185, v185, s4, v236
	v_exp_f32_e32 v185, v185
	v_add_f32_e32 v202, v202, v78
	v_add_f32_e32 v202, v202, v79
	v_mfma_f32_32x32x16_bf16 v[18:33], v[66:69], v[138:141], v[18:33]
	v_med3_f32 v186, v186, s4, v236
	v_exp_f32_e32 v186, v186
	v_med3_f32 v187, v187, s4, v236
	v_exp_f32_e32 v187, v187
	v_add_f32_e32 v202, v202, v80
	v_add_f32_e32 v202, v202, v81
	v_mfma_f32_32x32x16_bf16 v[2:17], v[66:69], v[142:145], v[2:17]
	v_med3_f32 v188, v188, s4, v236
	v_exp_f32_e32 v188, v188
	v_med3_f32 v189, v189, s4, v236
	v_exp_f32_e32 v189, v189
	v_cvt_pk_bf16_f32 v70, v74, v75
	v_cvt_pk_bf16_f32 v71, v76, v77
	v_cvt_pk_bf16_f32 v72, v78, v79
	v_cvt_pk_bf16_f32 v73, v80, v81
	ds_read_b128 v[214:217], v201 offset:24576
	ds_read_b128 v[224:227], v201 offset:28672
	ds_read_b128 v[240:243], v201 offset:32768
	ds_read_b128 v[244:247], v201 offset:36864
	s_waitcnt lgkmcnt(8)
	v_mfma_f32_32x32x16_bf16 v[50:65], v[70:73], v[146:149], v[50:65]
	v_med3_f32 v190, v190, s4, v236
	v_exp_f32_e32 v190, v190
	v_med3_f32 v191, v191, s4, v236
	v_exp_f32_e32 v191, v191
	v_add_f32_e32 v203, v182, v183
	v_add_f32_e32 v203, v203, v184
	v_mfma_f32_32x32x16_bf16 v[34:49], v[70:73], v[150:153], v[34:49]
	v_med3_f32 v192, v192, s4, v236
	v_exp_f32_e32 v192, v192
	v_med3_f32 v193, v193, s4, v236
	v_exp_f32_e32 v193, v193
	v_add_f32_e32 v203, v203, v185
	v_add_f32_e32 v203, v203, v186
	v_mfma_f32_32x32x16_bf16 v[18:33], v[70:73], v[154:157], v[18:33]
	v_med3_f32 v194, v194, s4, v236
	v_exp_f32_e32 v194, v194
	v_med3_f32 v195, v195, s4, v236
	v_exp_f32_e32 v195, v195
	v_add_f32_e32 v203, v203, v187
	v_mfma_f32_32x32x16_bf16 v[2:17], v[70:73], v[158:161], v[2:17]
	v_med3_f32 v196, v196, s4, v236
	v_exp_f32_e32 v196, v196
	v_med3_f32 v197, v197, s4, v236
	v_exp_f32_e32 v197, v197
	v_add_f32_e32 v203, v203, v188
	v_cvt_pk_bf16_f32 v182, v182, v183
	v_cvt_pk_bf16_f32 v183, v184, v185
	v_cvt_pk_bf16_f32 v184, v186, v187
	v_cvt_pk_bf16_f32 v185, v188, v189
	v_add_f32_e32 v203, v203, v189
	s_setprio 0
	s_waitcnt lgkmcnt(4)
	v_mfma_f32_32x32x16_bf16 v[50:65], v[182:185], v[162:165], v[50:65]
	v_add_f32_e32 v203, v203, v190
	v_add_f32_e32 v203, v203, v191
	v_add_f32_e32 v203, v203, v192
	v_mfma_f32_32x32x16_bf16 v[34:49], v[182:185], v[166:169], v[34:49]
	v_add_f32_e32 v203, v203, v193
	v_add_f32_e32 v203, v203, v194
	v_add_f32_e32 v203, v203, v195
	v_mfma_f32_32x32x16_bf16 v[18:33], v[182:185], v[170:173], v[18:33]
	v_add_f32_e32 v203, v203, v196
	v_add_f32_e32 v203, v203, v197
	v_cvt_pk_bf16_f32 v186, v190, v191
	v_cvt_pk_bf16_f32 v187, v192, v193
	v_cvt_pk_bf16_f32 v188, v194, v195
	v_cvt_pk_bf16_f32 v189, v196, v197
	v_mfma_f32_32x32x16_bf16 v[2:17], v[182:185], v[176:179], v[2:17]
	v_add_f32_e32 v202, v202, v203
	v_add_f32_e32 v0, v0, v202
	s_mov_b32 s100, 1
	s_waitcnt vmcnt(5) lgkmcnt(0)
	s_branch .LBB0_573
.Lat2_nodma:
	s_setprio 3
	s_mul_i32 s10, s28, 0xa000
	v_add_u32_e32 v198, s10, v218
	v_add_u32_e32 v199, s10, v219
	v_add_u32_e32 v200, s10, v209
	v_add_u32_e32 v201, s10, v208
	ds_read_b128 v[130:133], v198 offset:0
	ds_read_b128 v[134:137], v199 offset:0
	ds_read_b128 v[138:141], v200 offset:0
	ds_read_b128 v[142:145], v201 offset:0
	ds_read_b128 v[146:149], v198 offset:8192
	ds_read_b128 v[150:153], v199 offset:8192
	ds_read_b128 v[154:157], v200 offset:8192
	ds_read_b128 v[158:161], v201 offset:8192
	ds_read_b128 v[162:165], v198 offset:16384
	ds_read_b128 v[166:169], v199 offset:16384
	ds_read_b128 v[170:173], v200 offset:16384
	ds_read_b128 v[176:179], v201 offset:16384
	s_cmp_eq_u32 s100, 0
	s_cbranch_scc1 .Lat2_nopend2
	v_mfma_f32_32x32x16_bf16 v[50:65], v[186:189], v[214:217], v[50:65]
	v_mfma_f32_32x32x16_bf16 v[34:49], v[186:189], v[224:227], v[34:49]
	v_mfma_f32_32x32x16_bf16 v[18:33], v[186:189], v[240:243], v[18:33]
	v_mfma_f32_32x32x16_bf16 v[2:17], v[186:189], v[244:247], v[2:17]
.Lat2_nopend2:
	s_waitcnt lgkmcnt(8)
	v_mfma_f32_32x32x16_bf16 v[66:81], v[130:133], v[118:121], 0
	v_mfma_f32_32x32x16_bf16 v[66:81], v[134:137], v[114:117], v[66:81]
	v_mfma_f32_32x32x16_bf16 v[66:81], v[138:141], v[110:113], v[66:81]
	v_mfma_f32_32x32x16_bf16 v[66:81], v[142:145], v[106:109], v[66:81]
	ds_read_b128 v[130:133], v198 offset:4096
	ds_read_b128 v[134:137], v199 offset:4096
	ds_read_b128 v[138:141], v200 offset:4096
	ds_read_b128 v[142:145], v201 offset:4096
	s_waitcnt lgkmcnt(8)
	v_mfma_f32_32x32x16_bf16 v[66:81], v[146:149], v[102:105], v[66:81]
	v_mfma_f32_32x32x16_bf16 v[66:81], v[150:153], v[98:101], v[66:81]
	v_mfma_f32_32x32x16_bf16 v[66:81], v[154:157], v[94:97], v[66:81]
	v_mfma_f32_32x32x16_bf16 v[66:81], v[158:161], v[90:93], v[66:81]
	ds_read_b128 v[146:149], v198 offset:12288
	ds_read_b128 v[150:153], v199 offset:12288
	ds_read_b128 v[154:157], v200 offset:12288
	ds_read_b128 v[158:161], v201 offset:12288
	s_waitcnt lgkmcnt(8)
	v_mfma_f32_32x32x16_bf16 v[66:81], v[162:165], v[86:89], v[66:81]
	v_mfma_f32_32x32x16_bf16 v[66:81], v[166:169], v[126:129], v[66:81]
	v_mfma_f32_32x32x16_bf16 v[66:81], v[170:173], v[82:85], v[66:81]
	v_mfma_f32_32x32x16_bf16 v[66:81], v[176:179], v[122:125], v[66:81]
	s_setprio 2
	ds_read_b128 v[162:165], v198 offset:20480
	ds_read_b128 v[166:169], v199 offset:20480
	ds_read_b128 v[170:173], v200 offset:20480
	ds_read_b128 v[176:179], v201 offset:20480
	s_waitcnt lgkmcnt(8)
	v_mfma_f32_32x32x16_bf16 v[182:197], v[130:133], v[118:121], 0
	v_mfma_f32_32x32x16_bf16 v[182:197], v[134:137], v[114:117], v[182:197]
	v_mfma_f32_32x32x16_bf16 v[182:197], v[138:141], v[110:113], v[182:197]
	v_mfma_f32_32x32x16_bf16 v[182:197], v[142:145], v[106:109], v[182:197]
	ds_read_b128 v[130:133], v198 offset:24576
	ds_read_b128 v[134:137], v198 offset:28672
	ds_read_b128 v[138:141], v198 offset:32768
	ds_read_b128 v[142:145], v198 offset:36864
	s_waitcnt lgkmcnt(8)
	v_mfma_f32_32x32x16_bf16 v[182:197], v[146:149], v[102:105], v[182:197]
	v_med3_f32 v66, v66, s4, v236
	v_exp_f32_e32 v66, v66
	v_med3_f32 v67, v67, s4, v236
	v_exp_f32_e32 v67, v67
	v_mfma_f32_32x32x16_bf16 v[182:197], v[150:153], v[98:101], v[182:197]
	v_med3_f32 v68, v68, s4, v236
	v_exp_f32_e32 v68, v68
	v_med3_f32 v69, v69, s4, v236
	v_exp_f32_e32 v69, v69
	v_mfma_f32_32x32x16_bf16 v[182:197], v[154:157], v[94:97], v[182:197]
	v_med3_f32 v70, v70, s4, v236
	v_exp_f32_e32 v70, v70
	v_med3_f32 v71, v71, s4, v236
	v_exp_f32_e32 v71, v71
	v_mfma_f32_32x32x16_bf16 v[182:197], v[158:161], v[90:93], v[182:197]
	v_med3_f32 v72, v72, s4, v236
	v_exp_f32_e32 v72, v72
	v_med3_f32 v73, v73, s4, v236
	v_exp_f32_e32 v73, v73
	ds_read_b128 v[146:149], v199 offset:24576
	ds_read_b128 v[150:153], v199 offset:28672
	ds_read_b128 v[154:157], v199 offset:32768
	ds_read_b128 v[158:161], v199 offset:36864
	s_waitcnt lgkmcnt(8)
	v_mfma_f32_32x32x16_bf16 v[182:197], v[162:165], v[86:89], v[182:197]
	v_med3_f32 v74, v74, s4, v236
	v_exp_f32_e32 v74, v74
	v_med3_f32 v75, v75, s4, v236
	v_exp_f32_e32 v75, v75
	v_add_f32_e32 v202, v66, v67
	v_add_f32_e32 v202, v202, v68
	v_mfma_f32_32x32x16_bf16 v[182:197], v[166:169], v[126:129], v[182:197]
	v_med3_f32 v76, v76, s4, v236
	v_exp_f32_e32 v76, v76
	v_med3_f32 v77, v77, s4, v236
	v_exp_f32_e32 v77, v77
	v_add_f32_e32 v202, v202, v69
	v_add_f32_e32 v202, v202, v70
	v_mfma_f32_32x32x16_bf16 v[182:197], v[170:173], v[82:85], v[182:197]
	v_med3_f32 v78, v78, s4, v236
	v_exp_f32_e32 v78, v78
	v_med3_f32 v79, v79, s4, v236
	v_exp_f32_e32 v79, v79
	v_add_f32_e32 v202, v202, v71
	v_add_f32_e32 v202, v202, v72
	v_mfma_f32_32x32x16_bf16 v[182:197], v[176:179], v[122:125], v[182:197]
	v_med3_f32 v80, v80, s4, v236
	v_exp_f32_e32 v80, v80
	v_med3_f32 v81, v81, s4, v236
	v_exp_f32_e32 v81, v81
	v_add_f32_e32 v202, v202, v73
	s_setprio 1
	ds_read_b128 v[162:165], v200 offset:24576
	ds_read_b128 v[166:169], v200 offset:28672
	ds_read_b128 v[170:173], v200 offset:32768
	ds_read_b128 v[176:179], v200 offset:36864
	v_cvt_pk_bf16_f32 v66, v66, v67
	v_cvt_pk_bf16_f32 v67, v68, v69
	v_cvt_pk_bf16_f32 v68, v70, v71
	v_cvt_pk_bf16_f32 v69, v72, v73
	v_add_f32_e32 v202, v202, v74
	v_add_f32_e32 v202, v202, v75
	s_waitcnt lgkmcnt(8)
	v_mfma_f32_32x32x16_bf16 v[50:65], v[66:69], v[130:133], v[50:65]
	v_med3_f32 v182, v182, s4, v236
	v_exp_f32_e32 v182, v182
	v_med3_f32 v183, v183, s4, v236
	v_exp_f32_e32 v183, v183
	v_add_f32_e32 v202, v202, v76
	v_add_f32_e32 v202, v202, v77
	v_mfma_f32_32x32x16_bf16 v[34:49], v[66:69], v[134:137], v[34:49]
	v_med3_f32 v184, v184, s4, v236
	v_exp_f32_e32 v184, v184
	v_med3_f32 v185, v185, s4, v236
	v_exp_f32_e32 v185, v185
	v_add_f32_e32 v202, v202, v78
	v_add_f32_e32 v202, v202, v79
	v_mfma_f32_32x32x16_bf16 v[18:33], v[66:69], v[138:141], v[18:33]
	v_med3_f32 v186, v186, s4, v236
	v_exp_f32_e32 v186, v186
	v_med3_f32 v187, v187, s4, v236
	v_exp_f32_e32 v187, v187
	v_add_f32_e32 v202, v202, v80
	v_add_f32_e32 v202, v202, v81
	v_mfma_f32_32x32x16_bf16 v[2:17], v[66:69], v[142:145], v[2:17]
	v_med3_f32 v188, v188, s4, v236
	v_exp_f32_e32 v188, v188
	v_med3_f32 v189, v189, s4, v236
	v_exp_f32_e32 v189, v189
	v_cvt_pk_bf16_f32 v70, v74, v75
	v_cvt_pk_bf16_f32 v71, v76, v77
	v_cvt_pk_bf16_f32 v72, v78, v79
	v_cvt_pk_bf16_f32 v73, v80, v81
	ds_read_b128 v[214:217], v201 offset:24576
	ds_read_b128 v[224:227], v201 offset:28672
	ds_read_b128 v[240:243], v201 offset:32768
	ds_read_b128 v[244:247], v201 offset:36864
	s_waitcnt lgkmcnt(8)
	v_mfma_f32_32x32x16_bf16 v[50:65], v[70:73], v[146:149], v[50:65]
	v_med3_f32 v190, v190, s4, v236
	v_exp_f32_e32 v190, v190
	v_med3_f32 v191, v191, s4, v236
	v_exp_f32_e32 v191, v191
	v_add_f32_e32 v203, v182, v183
	v_add_f32_e32 v203, v203, v184
	v_mfma_f32_32x32x16_bf16 v[34:49], v[70:73], v[150:153], v[34:49]
	v_med3_f32 v192, v192, s4, v236
	v_exp_f32_e32 v192, v192
	v_med3_f32 v193, v193, s4, v236
	v_exp_f32_e32 v193, v193
	v_add_f32_e32 v203, v203, v185
	v_add_f32_e32 v203, v203, v186
	v_mfma_f32_32x32x16_bf16 v[18:33], v[70:73], v[154:157], v[18:33]
	v_med3_f32 v194, v194, s4, v236
	v_exp_f32_e32 v194, v194
	v_med3_f32 v195, v195, s4, v236
	v_exp_f32_e32 v195, v195
	v_add_f32_e32 v203, v203, v187
	v_mfma_f32_32x32x16_bf16 v[2:17], v[70:73], v[158:161], v[2:17]
	v_med3_f32 v196, v196, s4, v236
	v_exp_f32_e32 v196, v196
	v_med3_f32 v197, v197, s4, v236
	v_exp_f32_e32 v197, v197
	v_add_f32_e32 v203, v203, v188
	v_cvt_pk_bf16_f32 v182, v182, v183
	v_cvt_pk_bf16_f32 v183, v184, v185
	v_cvt_pk_bf16_f32 v184, v186, v187
	v_cvt_pk_bf16_f32 v185, v188, v189
	v_add_f32_e32 v203, v203, v189
	s_setprio 0
	s_waitcnt lgkmcnt(4)
	v_mfma_f32_32x32x16_bf16 v[50:65], v[182:185], v[162:165], v[50:65]
	v_add_f32_e32 v203, v203, v190
	v_add_f32_e32 v203, v203, v191
	v_add_f32_e32 v203, v203, v192
	v_mfma_f32_32x32x16_bf16 v[34:49], v[182:185], v[166:169], v[34:49]
	v_add_f32_e32 v203, v203, v193
	v_add_f32_e32 v203, v203, v194
	v_add_f32_e32 v203, v203, v195
	v_mfma_f32_32x32x16_bf16 v[18:33], v[182:185], v[170:173], v[18:33]
	v_add_f32_e32 v203, v203, v196
	v_add_f32_e32 v203, v203, v197
	v_cvt_pk_bf16_f32 v186, v190, v191
	v_cvt_pk_bf16_f32 v187, v192, v193
	v_cvt_pk_bf16_f32 v188, v194, v195
	v_cvt_pk_bf16_f32 v189, v196, v197
	v_mfma_f32_32x32x16_bf16 v[2:17], v[182:185], v[176:179], v[2:17]
	v_add_f32_e32 v202, v202, v203
	v_add_f32_e32 v0, v0, v202
	s_mov_b32 s100, 1
	s_waitcnt vmcnt(0) lgkmcnt(0)
	s_branch .LBB0_573

.LBB0_583:
	s_cmp_eq_u32 s100, 0
	s_cbranch_scc1 .Lat2_noflush
	v_mfma_f32_32x32x16_bf16 v[50:65], v[186:189], v[214:217], v[50:65]
	v_mfma_f32_32x32x16_bf16 v[34:49], v[186:189], v[224:227], v[34:49]
	v_mfma_f32_32x32x16_bf16 v[18:33], v[186:189], v[240:243], v[18:33]
	v_mfma_f32_32x32x16_bf16 v[2:17], v[186:189], v[244:247], v[2:17]
	s_mov_b32 s100, 0
	s_nop 15

	.amdhsa_kernel _Z6mk_fwd4Args
		.amdhsa_group_segment_fixed_size 0
		.amdhsa_private_segment_fixed_size 0
		.amdhsa_kernarg_size 560
		.amdhsa_user_sgpr_count 2
		.amdhsa_user_sgpr_dispatch_ptr 0
		.amdhsa_user_sgpr_queue_ptr 0
		.amdhsa_user_sgpr_kernarg_segment_ptr 1
		.amdhsa_user_sgpr_dispatch_id 0
		.amdhsa_user_sgpr_kernarg_preload_length 0
		.amdhsa_user_sgpr_kernarg_preload_offset 0
		.amdhsa_user_sgpr_private_segment_size 0
		.amdhsa_uses_dynamic_stack 0
		.amdhsa_enable_private_segment 0
		.amdhsa_system_sgpr_workgroup_id_x 1
		.amdhsa_system_sgpr_workgroup_id_y 0
		.amdhsa_system_sgpr_workgroup_id_z 0
		.amdhsa_system_sgpr_workgroup_info 0
		.amdhsa_system_vgpr_workitem_id 2
		.amdhsa_next_free_vgpr 256
		.amdhsa_next_free_sgpr 102
		.amdhsa_accum_offset 256
		.amdhsa_reserve_vcc 1
		.amdhsa_float_round_mode_32 0
		.amdhsa_float_round_mode_16_64 0
		.amdhsa_float_denorm_mode_32 3
		.amdhsa_float_denorm_mode_16_64 3
		.amdhsa_dx10_clamp 1
		.amdhsa_ieee_mode 1
		.amdhsa_fp16_overflow 0
		.amdhsa_tg_split 0
		.amdhsa_exception_fp_ieee_invalid_op 0
		.amdhsa_exception_fp_denorm_src 0
		.amdhsa_exception_fp_ieee_div_zero 0
		.amdhsa_exception_fp_ieee_overflow 0
		.amdhsa_exception_fp_ieee_underflow 0
		.amdhsa_exception_fp_ieee_inexact 0
		.amdhsa_exception_int_div_zero 0
	.end_amdhsa_kernel

amdhsa.kernels:
  - .agpr_count:     0
    .args:
      - .offset:         0
        .size:           304
        .value_kind:     by_value
      - .offset:         304
        .size:           4
        .value_kind:     hidden_block_count_x
      - .offset:         308
        .size:           4
        .value_kind:     hidden_block_count_y
      - .offset:         312
        .size:           4
        .value_kind:     hidden_block_count_z
      - .offset:         316
        .size:           2
        .value_kind:     hidden_group_size_x
      - .offset:         318
        .size:           2
        .value_kind:     hidden_group_size_y
      - .offset:         320
        .size:           2
        .value_kind:     hidden_group_size_z
      - .offset:         322
        .size:           2
        .value_kind:     hidden_remainder_x
      - .offset:         324
        .size:           2
        .value_kind:     hidden_remainder_y
      - .offset:         326
        .size:           2
        .value_kind:     hidden_remainder_z
      - .offset:         344
        .size:           8
        .value_kind:     hidden_global_offset_x
      - .offset:         352
        .size:           8
        .value_kind:     hidden_global_offset_y
      - .offset:         360
        .size:           8
        .value_kind:     hidden_global_offset_z
      - .offset:         368
        .size:           2
        .value_kind:     hidden_grid_dims
      - .offset:         392
        .size:           8
        .value_kind:     hidden_multigrid_sync_arg
      - .offset:         424
        .size:           4
        .value_kind:     hidden_dynamic_lds_size
    .group_segment_fixed_size: 0
    .kernarg_segment_align: 8
    .kernarg_segment_size: 560
    .language:       OpenCL C
    .language_version:
      - 2
      - 0
    .max_flat_workgroup_size: 512
    .name:           _Z6mk_fwd4Args
    .private_segment_fixed_size: 0
    .sgpr_count:     108
    .sgpr_spill_count: 94
    .symbol:         _Z6mk_fwd4Args.kd
    .uniform_work_group_size: 1
    .uses_dynamic_stack: false
    .vgpr_count:     256
    .vgpr_spill_count: 0
    .wavefront_size: 64
